# setprio 0 issued two MFMAs before the end of the segment instead of after the closing barrier
# baseline (speedup 1.0000x reference)
; #define PG8_STAGE(bufoff, gbase, voff) do { _Pragma("unroll") for (int _i = 0; _i < 2; ++_i) \
;         __builtin_amdgcn_global_load_lds((const unsigned*)((const char*)(gbase) + (voff)[_i]), (LAS unsigned*)(lds + (bufoff) + ldsw + _i * 8192), 16, 0, 0); } while (0)
; #define PG8_LDA(dst, b, h) do { _Pragma("unroll") for (int m = 0; m < 4; ++m) _Pragma("unroll") for (int k = 0; k < 2; ++k) dst[m][k] = *(const LAS bf16x8*)(lds + PG8_SA(b, h) + aoff + m * 2048 + k * 1024); } while (0)
; #define PG8_LDB(dst, b, h) do { _Pragma("unroll") for (int n = 0; n < 2; ++n) _Pragma("unroll") for (int k = 0; k < 2; ++k) dst[n][k] = *(const LAS bf16x8*)(lds + PG8_SB(b, h) + boff + n * 2048 + k * 1024); } while (0)
; #define PG8_MMA(ai, bj, At, Bt) do { __builtin_amdgcn_s_setprio(1); _Pragma("unroll") for (int m = 0; m < 4; ++m) _Pragma("unroll") for (int n = 0; n < 2; ++n) _Pragma("unroll") for (int k = 0; k < 2; ++k) \
;         acc[ai][bj][m][n] = __builtin_amdgcn_mfma_f32_16x16x32_bf16(Bt[n][k], At[m][k], acc[ai][bj][m][n], 0, 0, 0); __builtin_amdgcn_s_setprio(0); } while (0)
; #define PG8_WAIT_V(n) asm volatile("s_waitcnt vmcnt(" #n ")" ::: "memory")
; #define PG8_WAIT_L(n) asm volatile("s_waitcnt lgkmcnt(" #n ")" ::: "memory")
; #define PG8_BAR __builtin_amdgcn_s_barrier()
; #define PG8_SCHED __builtin_amdgcn_sched_barrier(0)
; template <class Epi, bool ALIGN_EPI, bool SP2 = PG8_SP2_DEFAULT>
; __device__ __forceinline__ void gemm_phase(LAS unsigned char* lds, const Gemm g, const StaticOrder& S, const Epi& E) {
;     ...
;             const bool last = (t == nt - 2);
;             const char* a1 = cA + (size_t)(t + 1) * kstep;
;             const char* a2 = last ? nA : cA + (size_t)(t + 2) * kstep; const char* b2 = last ? nB : cB + (size_t)(t + 2) * kstep;
;             const char* a3 = a2 + kstep; const char* b3 = b2 + kstep;
;             if constexpr (SP2) {
;             PG8_LDB(B0, 0, 0); PG8_LDB(B1, 0, 1); PG8_SCHED; PG8_LDA(At, 0, 0); PG8_STAGE(PG8_SA(1, 1), a1 + hstepA, voffA);
;             PG8_WAIT_V(8); PG8_WAIT_L(0); PG8_BAR; PG8_MMA(0, 0, At, B0); PG8_MMA(0, 1, At, B1); PG8_BAR; PG8_SCHED;
;             PG8_LDA(At, 0, 1); PG8_STAGE(PG8_SB(0, 0), b2, voffB); PG8_STAGE(PG8_SB(0, 1), b2 + hstepB, voffB); PG8_STAGE(PG8_SA(0, 0), a2, voffA);
;             PG8_WAIT_V(8); PG8_WAIT_L(0); PG8_BAR; PG8_MMA(1, 0, At, B0); PG8_MMA(1, 1, At, B1); PG8_BAR; PG8_SCHED;
.LBB0_250:
	ds_read_b128 v[150:153], v147
	ds_read_b128 v[154:157], v147 offset:1024
	ds_read_b128 v[158:161], v147 offset:2048
	ds_read_b128 v[162:165], v147 offset:3072
	ds_read_b128 v[166:169], v148
	ds_read_b128 v[170:173], v148 offset:1024
	ds_read_b128 v[174:177], v148 offset:2048
	ds_read_b128 v[178:181], v148 offset:3072
	s_add_u32 s20, s18, 0xfff00080
	s_addc_u32 s21, s19, -1
	s_cmp_eq_u32 s44, 60
	s_cselect_b32 s23, s13, s21
	s_cselect_b32 s22, s40, s20
	s_cselect_b32 s21, s11, s43
	s_cselect_b32 s20, s41, s42
	v_lshl_add_u64 v[206:207], s[18:19], 0, v[136:137]
	s_add_i32 m0, s9, 0xc000
	ds_read_b128 v[182:185], v149
	ds_read_b128 v[186:189], v149 offset:1024
	ds_read_b128 v[190:193], v149 offset:2048
	ds_read_b128 v[198:201], v149 offset:3072
	ds_read_b128 v[202:205], v149 offset:4096
	ds_read_b128 v[216:219], v149 offset:5120
	ds_read_b128 v[220:223], v149 offset:6144
	ds_read_b128 v[224:227], v149 offset:7168
	global_load_lds_dwordx4 v[206:207], off
	v_lshl_add_u64 v[206:207], s[18:19], 0, v[138:139]
	s_add_i32 m0, s9, 0xe000
	s_nop 0
	global_load_lds_dwordx4 v[206:207], off
	s_waitcnt vmcnt(8)
	s_waitcnt lgkmcnt(0)
	s_setprio 1
	s_barrier
	v_mfma_f32_16x16x32_bf16 v[124:127], v[150:153], v[182:185], v[124:127]
	v_mfma_f32_16x16x32_bf16 v[120:123], v[158:161], v[182:185], v[120:123]
	v_mfma_f32_16x16x32_bf16 v[116:119], v[150:153], v[190:193], v[116:119]
	v_mfma_f32_16x16x32_bf16 v[112:115], v[158:161], v[190:193], v[112:115]
	v_mfma_f32_16x16x32_bf16 v[100:103], v[150:153], v[202:205], v[100:103]
	v_mfma_f32_16x16x32_bf16 v[96:99], v[158:161], v[202:205], v[96:99]
	v_mfma_f32_16x16x32_bf16 v[84:87], v[150:153], v[220:223], v[84:87]
	v_mfma_f32_16x16x32_bf16 v[80:83], v[158:161], v[220:223], v[80:83]
	v_mfma_f32_16x16x32_bf16 v[124:127], v[154:157], v[186:189], v[124:127]
	v_mfma_f32_16x16x32_bf16 v[120:123], v[162:165], v[186:189], v[120:123]
	v_mfma_f32_16x16x32_bf16 v[116:119], v[154:157], v[198:201], v[116:119]
	v_mfma_f32_16x16x32_bf16 v[112:115], v[162:165], v[198:201], v[112:115]
	v_mfma_f32_16x16x32_bf16 v[100:103], v[154:157], v[216:219], v[100:103]
	v_mfma_f32_16x16x32_bf16 v[96:99], v[162:165], v[216:219], v[96:99]
	v_mfma_f32_16x16x32_bf16 v[84:87], v[154:157], v[224:227], v[84:87]
	v_mfma_f32_16x16x32_bf16 v[80:83], v[162:165], v[224:227], v[80:83]
	v_mfma_f32_16x16x32_bf16 v[108:111], v[166:169], v[182:185], v[108:111]
	v_mfma_f32_16x16x32_bf16 v[104:107], v[174:177], v[182:185], v[104:107]
	v_mfma_f32_16x16x32_bf16 v[92:95], v[166:169], v[190:193], v[92:95]
	v_mfma_f32_16x16x32_bf16 v[88:91], v[174:177], v[190:193], v[88:91]
	v_mfma_f32_16x16x32_bf16 v[76:79], v[166:169], v[202:205], v[76:79]
	v_mfma_f32_16x16x32_bf16 v[72:75], v[174:177], v[202:205], v[72:75]
	v_mfma_f32_16x16x32_bf16 v[68:71], v[166:169], v[220:223], v[68:71]
	v_mfma_f32_16x16x32_bf16 v[64:67], v[174:177], v[220:223], v[64:67]
	v_mfma_f32_16x16x32_bf16 v[108:111], v[170:173], v[186:189], v[108:111]
	v_mfma_f32_16x16x32_bf16 v[104:107], v[178:181], v[186:189], v[104:107]
	v_mfma_f32_16x16x32_bf16 v[92:95], v[170:173], v[198:201], v[92:95]
	v_mfma_f32_16x16x32_bf16 v[88:91], v[178:181], v[198:201], v[88:91]
	v_mfma_f32_16x16x32_bf16 v[76:79], v[170:173], v[216:219], v[76:79]
	v_mfma_f32_16x16x32_bf16 v[72:75], v[178:181], v[216:219], v[72:75]
	s_setprio 0
	v_mfma_f32_16x16x32_bf16 v[68:71], v[170:173], v[224:227], v[68:71]
	v_mfma_f32_16x16x32_bf16 v[64:67], v[178:181], v[224:227], v[64:67]
	s_barrier
	s_add_i32 s45, s36, s24
	v_lshl_add_u64 v[206:207], s[20:21], 0, v[132:133]
	s_mov_b32 m0, s45
	ds_read_b128 v[182:185], v149 offset:16384
	ds_read_b128 v[186:189], v149 offset:17408
	ds_read_b128 v[190:193], v149 offset:18432
	ds_read_b128 v[198:201], v149 offset:19456
	ds_read_b128 v[202:205], v149 offset:20480
	ds_read_b128 v[216:219], v149 offset:21504
	ds_read_b128 v[220:223], v149 offset:22528
	ds_read_b128 v[224:227], v149 offset:23552
	global_load_lds_dwordx4 v[206:207], off
	s_add_i32 m0, s45, 0x2000
	s_add_u32 s46, s20, 0x100000
	v_lshl_add_u64 v[210:211], s[20:21], 0, v[128:129]
	s_addc_u32 s47, s21, 0
	s_add_i32 s45, s37, s24
	global_load_lds_dwordx4 v[210:211], off
	v_lshl_add_u64 v[228:229], s[46:47], 0, v[132:133]
	s_mov_b32 m0, s45
	v_lshl_add_u64 v[230:231], s[22:23], 0, v[130:131]
	global_load_lds_dwordx4 v[228:229], off
	v_lshl_add_u64 v[228:229], s[46:47], 0, v[128:129]
	s_add_i32 m0, s45, 0x2000
	s_nop 0
	global_load_lds_dwordx4 v[228:229], off
	v_lshl_add_u64 v[228:229], s[22:23], 0, v[134:135]
	s_mov_b32 m0, s9
	s_nop 0
	global_load_lds_dwordx4 v[228:229], off
	s_mov_b32 m0, s27
	s_nop 0
	global_load_lds_dwordx4 v[230:231], off
	s_waitcnt vmcnt(8)
	s_waitcnt lgkmcnt(0)
	s_setprio 1
	s_barrier
; #define PG8_STAGE(bufoff, gbase, voff) do { _Pragma("unroll") for (int _i = 0; _i < 2; ++_i) \
;         __builtin_amdgcn_global_load_lds((const unsigned*)((const char*)(gbase) + (voff)[_i]), (LAS unsigned*)(lds + (bufoff) + ldsw + _i * 8192), 16, 0, 0); } while (0)
; #define PG8_LDA(dst, b, h) do { _Pragma("unroll") for (int m = 0; m < 4; ++m) _Pragma("unroll") for (int k = 0; k < 2; ++k) dst[m][k] = *(const LAS bf16x8*)(lds + PG8_SA(b, h) + aoff + m * 2048 + k * 1024); } while (0)
; #define PG8_LDB(dst, b, h) do { _Pragma("unroll") for (int n = 0; n < 2; ++n) _Pragma("unroll") for (int k = 0; k < 2; ++k) dst[n][k] = *(const LAS bf16x8*)(lds + PG8_SB(b, h) + boff + n * 2048 + k * 1024); } while (0)
; #define PG8_MMA(ai, bj, At, Bt) do { __builtin_amdgcn_s_setprio(1); _Pragma("unroll") for (int m = 0; m < 4; ++m) _Pragma("unroll") for (int n = 0; n < 2; ++n) _Pragma("unroll") for (int k = 0; k < 2; ++k) \
;         acc[ai][bj][m][n] = __builtin_amdgcn_mfma_f32_16x16x32_bf16(Bt[n][k], At[m][k], acc[ai][bj][m][n], 0, 0, 0); __builtin_amdgcn_s_setprio(0); } while (0)
; #define PG8_WAIT_V(n) asm volatile("s_waitcnt vmcnt(" #n ")" ::: "memory")
; #define PG8_WAIT_L(n) asm volatile("s_waitcnt lgkmcnt(" #n ")" ::: "memory")
; #define PG8_BAR __builtin_amdgcn_s_barrier()
; #define PG8_SCHED __builtin_amdgcn_sched_barrier(0)
; template <class Epi, bool ALIGN_EPI, bool SP2 = PG8_SP2_DEFAULT>
; __device__ __forceinline__ void gemm_phase(LAS unsigned char* lds, const Gemm g, const StaticOrder& S, const Epi& E) {
;     ...
;             PG8_WAIT_V(8); PG8_WAIT_L(0); PG8_BAR; PG8_MMA(1, 0, At, B0); PG8_MMA(1, 1, At, B1); PG8_BAR; PG8_SCHED;
;             PG8_LDB(B0, 1, 0); PG8_LDB(B1, 1, 1); PG8_SCHED; PG8_LDA(At, 1, 0); PG8_STAGE(PG8_SA(0, 1), a2 + hstepA, voffA);
;             PG8_WAIT_V(8); PG8_WAIT_L(0); PG8_BAR; PG8_MMA(0, 0, At, B0); PG8_MMA(0, 1, At, B1); PG8_BAR; PG8_SCHED;
	v_mfma_f32_16x16x32_bf16 v[60:63], v[150:153], v[182:185], v[60:63]
	v_mfma_f32_16x16x32_bf16 v[56:59], v[158:161], v[182:185], v[56:59]
	v_mfma_f32_16x16x32_bf16 v[52:55], v[150:153], v[190:193], v[52:55]
	v_mfma_f32_16x16x32_bf16 v[48:51], v[158:161], v[190:193], v[48:51]
	v_mfma_f32_16x16x32_bf16 v[36:39], v[150:153], v[202:205], v[36:39]
	v_mfma_f32_16x16x32_bf16 v[32:35], v[158:161], v[202:205], v[32:35]
	v_mfma_f32_16x16x32_bf16 v[20:23], v[150:153], v[220:223], v[20:23]
	v_mfma_f32_16x16x32_bf16 v[16:19], v[158:161], v[220:223], v[16:19]
	v_mfma_f32_16x16x32_bf16 v[60:63], v[154:157], v[186:189], v[60:63]
	v_mfma_f32_16x16x32_bf16 v[56:59], v[162:165], v[186:189], v[56:59]
	v_mfma_f32_16x16x32_bf16 v[52:55], v[154:157], v[198:201], v[52:55]
	v_mfma_f32_16x16x32_bf16 v[48:51], v[162:165], v[198:201], v[48:51]
	v_mfma_f32_16x16x32_bf16 v[36:39], v[154:157], v[216:219], v[36:39]
	v_mfma_f32_16x16x32_bf16 v[32:35], v[162:165], v[216:219], v[32:35]
	v_mfma_f32_16x16x32_bf16 v[20:23], v[154:157], v[224:227], v[20:23]
	v_mfma_f32_16x16x32_bf16 v[16:19], v[162:165], v[224:227], v[16:19]
	v_mfma_f32_16x16x32_bf16 v[44:47], v[166:169], v[182:185], v[44:47]
	v_mfma_f32_16x16x32_bf16 v[40:43], v[174:177], v[182:185], v[40:43]
	v_mfma_f32_16x16x32_bf16 v[28:31], v[166:169], v[190:193], v[28:31]
	v_mfma_f32_16x16x32_bf16 v[24:27], v[174:177], v[190:193], v[24:27]
	v_mfma_f32_16x16x32_bf16 v[12:15], v[166:169], v[202:205], v[12:15]
	v_mfma_f32_16x16x32_bf16 v[8:11], v[174:177], v[202:205], v[8:11]
	v_mfma_f32_16x16x32_bf16 v[4:7], v[166:169], v[220:223], v[4:7]
	v_mfma_f32_16x16x32_bf16 v[0:3], v[174:177], v[220:223], v[0:3]
	v_mfma_f32_16x16x32_bf16 v[44:47], v[170:173], v[186:189], v[44:47]
	v_mfma_f32_16x16x32_bf16 v[40:43], v[178:181], v[186:189], v[40:43]
	v_mfma_f32_16x16x32_bf16 v[28:31], v[170:173], v[198:201], v[28:31]
	v_mfma_f32_16x16x32_bf16 v[24:27], v[178:181], v[198:201], v[24:27]
	v_mfma_f32_16x16x32_bf16 v[12:15], v[170:173], v[216:219], v[12:15]
	v_mfma_f32_16x16x32_bf16 v[8:11], v[178:181], v[216:219], v[8:11]
	s_setprio 0
	v_mfma_f32_16x16x32_bf16 v[4:7], v[170:173], v[224:227], v[4:7]
	v_mfma_f32_16x16x32_bf16 v[0:3], v[178:181], v[224:227], v[0:3]
	s_barrier
	s_add_i32 s45, 0, 0x18000
	s_add_i32 s46, 0, 0x1c000
	v_add_u32_e32 v162, s45, v145
	v_add_u32_e32 v178, s46, v145
	ds_read_b128 v[150:153], v162
	ds_read_b128 v[154:157], v162 offset:1024
	ds_read_b128 v[158:161], v162 offset:2048
	ds_read_b128 v[162:165], v162 offset:3072
	ds_read_b128 v[166:169], v178
	ds_read_b128 v[170:173], v178 offset:1024
	ds_read_b128 v[174:177], v178 offset:2048
	ds_read_b128 v[178:181], v178 offset:3072
	s_add_u32 s22, s22, 0x100000
	s_addc_u32 s23, s23, 0
	s_mov_b32 m0, s28
	v_lshl_add_u64 v[232:233], s[22:23], 0, v[134:135]
	ds_read_b128 v[182:185], v149 offset:32768
	ds_read_b128 v[186:189], v149 offset:33792
	ds_read_b128 v[190:193], v149 offset:34816
	ds_read_b128 v[198:201], v149 offset:35840
	ds_read_b128 v[202:205], v149 offset:36864
	ds_read_b128 v[216:219], v149 offset:37888
	ds_read_b128 v[220:223], v149 offset:38912
	ds_read_b128 v[224:227], v149 offset:39936
	global_load_lds_dwordx4 v[232:233], off
	v_lshl_add_u64 v[232:233], s[22:23], 0, v[130:131]
	s_mov_b32 m0, s29
	s_nop 0
	global_load_lds_dwordx4 v[232:233], off
	s_waitcnt vmcnt(8)
	s_waitcnt lgkmcnt(0)
	s_setprio 1
	s_barrier
	v_mfma_f32_16x16x32_bf16 v[124:127], v[150:153], v[182:185], v[124:127]
	v_mfma_f32_16x16x32_bf16 v[120:123], v[158:161], v[182:185], v[120:123]
	v_mfma_f32_16x16x32_bf16 v[116:119], v[150:153], v[190:193], v[116:119]
	v_mfma_f32_16x16x32_bf16 v[112:115], v[158:161], v[190:193], v[112:115]
	v_mfma_f32_16x16x32_bf16 v[100:103], v[150:153], v[202:205], v[100:103]
	v_mfma_f32_16x16x32_bf16 v[96:99], v[158:161], v[202:205], v[96:99]
	v_mfma_f32_16x16x32_bf16 v[84:87], v[150:153], v[220:223], v[84:87]
	v_mfma_f32_16x16x32_bf16 v[80:83], v[158:161], v[220:223], v[80:83]
	v_mfma_f32_16x16x32_bf16 v[124:127], v[154:157], v[186:189], v[124:127]
	v_mfma_f32_16x16x32_bf16 v[120:123], v[162:165], v[186:189], v[120:123]
	v_mfma_f32_16x16x32_bf16 v[116:119], v[154:157], v[198:201], v[116:119]
	v_mfma_f32_16x16x32_bf16 v[112:115], v[162:165], v[198:201], v[112:115]
	v_mfma_f32_16x16x32_bf16 v[100:103], v[154:157], v[216:219], v[100:103]
	v_mfma_f32_16x16x32_bf16 v[96:99], v[162:165], v[216:219], v[96:99]
	v_mfma_f32_16x16x32_bf16 v[84:87], v[154:157], v[224:227], v[84:87]
	v_mfma_f32_16x16x32_bf16 v[80:83], v[162:165], v[224:227], v[80:83]
	v_mfma_f32_16x16x32_bf16 v[108:111], v[166:169], v[182:185], v[108:111]
	v_mfma_f32_16x16x32_bf16 v[104:107], v[174:177], v[182:185], v[104:107]
	v_mfma_f32_16x16x32_bf16 v[92:95], v[166:169], v[190:193], v[92:95]
	v_mfma_f32_16x16x32_bf16 v[88:91], v[174:177], v[190:193], v[88:91]
	v_mfma_f32_16x16x32_bf16 v[76:79], v[166:169], v[202:205], v[76:79]
	v_mfma_f32_16x16x32_bf16 v[72:75], v[174:177], v[202:205], v[72:75]
	v_mfma_f32_16x16x32_bf16 v[68:71], v[166:169], v[220:223], v[68:71]
	v_mfma_f32_16x16x32_bf16 v[64:67], v[174:177], v[220:223], v[64:67]
	v_mfma_f32_16x16x32_bf16 v[108:111], v[170:173], v[186:189], v[108:111]
	v_mfma_f32_16x16x32_bf16 v[104:107], v[178:181], v[186:189], v[104:107]
	v_mfma_f32_16x16x32_bf16 v[92:95], v[170:173], v[198:201], v[92:95]
	v_mfma_f32_16x16x32_bf16 v[88:91], v[178:181], v[198:201], v[88:91]
	v_mfma_f32_16x16x32_bf16 v[76:79], v[170:173], v[216:219], v[76:79]
	v_mfma_f32_16x16x32_bf16 v[72:75], v[178:181], v[216:219], v[72:75]
	s_setprio 0
	v_mfma_f32_16x16x32_bf16 v[68:71], v[170:173], v[224:227], v[68:71]
	v_mfma_f32_16x16x32_bf16 v[64:67], v[178:181], v[224:227], v[64:67]
	s_barrier
; #define PG8_STAGE(bufoff, gbase, voff) do { _Pragma("unroll") for (int _i = 0; _i < 2; ++_i) \
;         __builtin_amdgcn_global_load_lds((const unsigned*)((const char*)(gbase) + (voff)[_i]), (LAS unsigned*)(lds + (bufoff) + ldsw + _i * 8192), 16, 0, 0); } while (0)
; #define PG8_LDA(dst, b, h) do { _Pragma("unroll") for (int m = 0; m < 4; ++m) _Pragma("unroll") for (int k = 0; k < 2; ++k) dst[m][k] = *(const LAS bf16x8*)(lds + PG8_SA(b, h) + aoff + m * 2048 + k * 1024); } while (0)
; #define PG8_MMA(ai, bj, At, Bt) do { __builtin_amdgcn_s_setprio(1); _Pragma("unroll") for (int m = 0; m < 4; ++m) _Pragma("unroll") for (int n = 0; n < 2; ++n) _Pragma("unroll") for (int k = 0; k < 2; ++k) \
;         acc[ai][bj][m][n] = __builtin_amdgcn_mfma_f32_16x16x32_bf16(Bt[n][k], At[m][k], acc[ai][bj][m][n], 0, 0, 0); __builtin_amdgcn_s_setprio(0); } while (0)
; #define PG8_WAIT_V(n) asm volatile("s_waitcnt vmcnt(" #n ")" ::: "memory")
; #define PG8_WAIT_L(n) asm volatile("s_waitcnt lgkmcnt(" #n ")" ::: "memory")
; #define PG8_BAR __builtin_amdgcn_s_barrier()
; #define PG8_SCHED __builtin_amdgcn_sched_barrier(0)
; template <class Epi, bool ALIGN_EPI, bool SP2 = PG8_SP2_DEFAULT>
; __device__ __forceinline__ void gemm_phase(LAS unsigned char* lds, const Gemm g, const StaticOrder& S, const Epi& E) {
;     ...
;         for (int t = 0; t < nt; t += 2) {
;             const bool last = (t == nt - 2);
;     ...
;             PG8_LDA(At, 1, 1); PG8_STAGE(PG8_SB(1, 0), b3, voffB); PG8_STAGE(PG8_SB(1, 1), b3 + hstepB, voffB); PG8_STAGE(PG8_SA(1, 0), a3, voffA);
;             PG8_WAIT_V(8); PG8_WAIT_L(0); PG8_BAR; PG8_MMA(1, 0, At, B0); PG8_MMA(1, 1, At, B1); PG8_BAR; PG8_SCHED;
	s_add_i32 s22, s45, s24
	v_lshl_add_u64 v[206:207], v[206:207], 0, s[4:5]
	s_mov_b32 m0, s22
	ds_read_b128 v[182:185], v149 offset:49152
	ds_read_b128 v[186:189], v149 offset:50176
	ds_read_b128 v[190:193], v149 offset:51200
	ds_read_b128 v[198:201], v149 offset:52224
	ds_read_b128 v[202:205], v149 offset:53248
	ds_read_b128 v[216:219], v149 offset:54272
	ds_read_b128 v[220:223], v149 offset:55296
	ds_read_b128 v[224:227], v149 offset:56320
	global_load_lds_dwordx4 v[206:207], off
	s_add_i32 m0, s22, 0x2000
	s_add_u32 s20, s20, 0x100080
	v_lshl_add_u64 v[206:207], v[210:211], 0, s[4:5]
	s_addc_u32 s21, s21, 0
	s_add_i32 s22, s46, s24
	global_load_lds_dwordx4 v[206:207], off
	v_lshl_add_u64 v[206:207], s[20:21], 0, v[132:133]
	s_mov_b32 m0, s22
	s_nop 0
	global_load_lds_dwordx4 v[206:207], off
	v_lshl_add_u64 v[206:207], s[20:21], 0, v[128:129]
	s_add_i32 m0, s22, 0x2000
	s_nop 0
	global_load_lds_dwordx4 v[206:207], off
	v_lshl_add_u64 v[206:207], v[228:229], 0, s[4:5]
	s_mov_b32 m0, s33
	s_nop 0
	global_load_lds_dwordx4 v[206:207], off
	v_lshl_add_u64 v[206:207], v[230:231], 0, s[4:5]
	s_mov_b32 m0, s34
	s_nop 0
	global_load_lds_dwordx4 v[206:207], off
	s_waitcnt vmcnt(8)
	s_waitcnt lgkmcnt(0)
	s_setprio 1
	s_barrier
	v_mfma_f32_16x16x32_bf16 v[60:63], v[150:153], v[182:185], v[60:63]
	v_mfma_f32_16x16x32_bf16 v[56:59], v[158:161], v[182:185], v[56:59]
	v_mfma_f32_16x16x32_bf16 v[52:55], v[150:153], v[190:193], v[52:55]
	v_mfma_f32_16x16x32_bf16 v[48:51], v[158:161], v[190:193], v[48:51]
	v_mfma_f32_16x16x32_bf16 v[36:39], v[150:153], v[202:205], v[36:39]
	v_mfma_f32_16x16x32_bf16 v[32:35], v[158:161], v[202:205], v[32:35]
	v_mfma_f32_16x16x32_bf16 v[20:23], v[150:153], v[220:223], v[20:23]
	v_mfma_f32_16x16x32_bf16 v[16:19], v[158:161], v[220:223], v[16:19]
	v_mfma_f32_16x16x32_bf16 v[60:63], v[154:157], v[186:189], v[60:63]
	v_mfma_f32_16x16x32_bf16 v[56:59], v[162:165], v[186:189], v[56:59]
	v_mfma_f32_16x16x32_bf16 v[52:55], v[154:157], v[198:201], v[52:55]
	v_mfma_f32_16x16x32_bf16 v[48:51], v[162:165], v[198:201], v[48:51]
	v_mfma_f32_16x16x32_bf16 v[36:39], v[154:157], v[216:219], v[36:39]
	v_mfma_f32_16x16x32_bf16 v[32:35], v[162:165], v[216:219], v[32:35]
	v_mfma_f32_16x16x32_bf16 v[20:23], v[154:157], v[224:227], v[20:23]
	v_mfma_f32_16x16x32_bf16 v[16:19], v[162:165], v[224:227], v[16:19]
	v_mfma_f32_16x16x32_bf16 v[44:47], v[166:169], v[182:185], v[44:47]
	v_mfma_f32_16x16x32_bf16 v[40:43], v[174:177], v[182:185], v[40:43]
	v_mfma_f32_16x16x32_bf16 v[28:31], v[166:169], v[190:193], v[28:31]
	v_mfma_f32_16x16x32_bf16 v[24:27], v[174:177], v[190:193], v[24:27]
	v_mfma_f32_16x16x32_bf16 v[12:15], v[166:169], v[202:205], v[12:15]
	v_mfma_f32_16x16x32_bf16 v[8:11], v[174:177], v[202:205], v[8:11]
	v_mfma_f32_16x16x32_bf16 v[4:7], v[166:169], v[220:223], v[4:7]
	v_mfma_f32_16x16x32_bf16 v[0:3], v[174:177], v[220:223], v[0:3]
	v_mfma_f32_16x16x32_bf16 v[44:47], v[170:173], v[186:189], v[44:47]
	v_mfma_f32_16x16x32_bf16 v[40:43], v[178:181], v[186:189], v[40:43]
	v_mfma_f32_16x16x32_bf16 v[28:31], v[170:173], v[198:201], v[28:31]
	v_mfma_f32_16x16x32_bf16 v[24:27], v[178:181], v[198:201], v[24:27]
	v_mfma_f32_16x16x32_bf16 v[12:15], v[170:173], v[216:219], v[12:15]
	v_mfma_f32_16x16x32_bf16 v[8:11], v[178:181], v[216:219], v[8:11]
	s_setprio 0
	v_mfma_f32_16x16x32_bf16 v[4:7], v[170:173], v[224:227], v[4:7]
	v_mfma_f32_16x16x32_bf16 v[0:3], v[178:181], v[224:227], v[0:3]
	s_barrier
	s_add_i32 s44, s44, 2
	s_add_u32 s18, s18, 0x100
	s_addc_u32 s19, s19, 0
	s_add_u32 s42, s42, 0x100
	s_addc_u32 s43, s43, 0
	s_cmp_gt_u32 s44, 61
	s_cbranch_scc0 .LBB0_250
	s_and_b64 vcc, exec, s[6:7]
	s_cbranch_vccz .LBB0_253
	s_barrier

; #define PG8_STAGE(bufoff, gbase, voff) do { _Pragma("unroll") for (int _i = 0; _i < 2; ++_i) \
;         __builtin_amdgcn_global_load_lds((const unsigned*)((const char*)(gbase) + (voff)[_i]), (LAS unsigned*)(lds + (bufoff) + ldsw + _i * 8192), 16, 0, 0); } while (0)
; #define PG8_LDA(dst, b, h) do { _Pragma("unroll") for (int m = 0; m < 4; ++m) _Pragma("unroll") for (int k = 0; k < 2; ++k) dst[m][k] = *(const LAS bf16x8*)(lds + PG8_SA(b, h) + aoff + m * 2048 + k * 1024); } while (0)
; #define PG8_LDB(dst, b, h) do { _Pragma("unroll") for (int n = 0; n < 2; ++n) _Pragma("unroll") for (int k = 0; k < 2; ++k) dst[n][k] = *(const LAS bf16x8*)(lds + PG8_SB(b, h) + boff + n * 2048 + k * 1024); } while (0)
; #define PG8_MMA(ai, bj, At, Bt) do { __builtin_amdgcn_s_setprio(1); _Pragma("unroll") for (int m = 0; m < 4; ++m) _Pragma("unroll") for (int n = 0; n < 2; ++n) _Pragma("unroll") for (int k = 0; k < 2; ++k) \
;         acc[ai][bj][m][n] = __builtin_amdgcn_mfma_f32_16x16x32_bf16(Bt[n][k], At[m][k], acc[ai][bj][m][n], 0, 0, 0); __builtin_amdgcn_s_setprio(0); } while (0)
; #define PG8_WAIT_V(n) asm volatile("s_waitcnt vmcnt(" #n ")" ::: "memory")
; #define PG8_WAIT_L(n) asm volatile("s_waitcnt lgkmcnt(" #n ")" ::: "memory")
; #define PG8_BAR __builtin_amdgcn_s_barrier()
; #define PG8_SCHED __builtin_amdgcn_sched_barrier(0)
; template <class Epi, bool ALIGN_EPI, bool SP2 = PG8_SP2_DEFAULT>
; __device__ __forceinline__ void gemm_phase(LAS unsigned char* lds, const Gemm g, const StaticOrder& S, const Epi& E) {
;     ...
;             const bool last = (t == nt - 2);
;             const char* a1 = cA + (size_t)(t + 1) * kstep;
;             const char* a2 = last ? nA : cA + (size_t)(t + 2) * kstep; const char* b2 = last ? nB : cB + (size_t)(t + 2) * kstep;
;             const char* a3 = a2 + kstep; const char* b3 = b2 + kstep;
;             if constexpr (SP2) {
;             PG8_LDB(B0, 0, 0); PG8_LDB(B1, 0, 1); PG8_SCHED; PG8_LDA(At, 0, 0); PG8_STAGE(PG8_SA(1, 1), a1 + hstepA, voffA);
;             PG8_WAIT_V(8); PG8_WAIT_L(0); PG8_BAR; PG8_MMA(0, 0, At, B0); PG8_MMA(0, 1, At, B1); PG8_BAR; PG8_SCHED;
;             PG8_LDA(At, 0, 1); PG8_STAGE(PG8_SB(0, 0), b2, voffB); PG8_STAGE(PG8_SB(0, 1), b2 + hstepB, voffB); PG8_STAGE(PG8_SA(0, 0), a2, voffA);
;             PG8_WAIT_V(8); PG8_WAIT_L(0); PG8_BAR; PG8_MMA(1, 0, At, B0); PG8_MMA(1, 1, At, B1); PG8_BAR; PG8_SCHED;
.LBB0_428:
	ds_read_b128 v[128:131], v165
	ds_read_b128 v[132:135], v165 offset:1024
	ds_read_b128 v[136:139], v165 offset:2048
	ds_read_b128 v[140:143], v165 offset:3072
	ds_read_b128 v[168:171], v166
	ds_read_b128 v[172:175], v166 offset:1024
	ds_read_b128 v[176:179], v166 offset:2048
	ds_read_b128 v[180:183], v166 offset:3072
	s_add_u32 s24, s22, 0xfffe0080
	s_addc_u32 s25, s23, -1
	s_cmp_eq_u32 s51, 4
	s_cselect_b32 s27, s15, s25
	s_cselect_b32 s26, s47, s24
	s_cselect_b32 s25, s13, s50
	s_cselect_b32 s24, s48, s49
	v_lshl_add_u64 v[160:161], s[22:23], 0, v[152:153]
	s_add_i32 m0, s21, 0xc000
	ds_read_b128 v[184:187], v167
	ds_read_b128 v[188:191], v167 offset:1024
	ds_read_b128 v[198:201], v167 offset:2048
	ds_read_b128 v[202:205], v167 offset:3072
	ds_read_b128 v[216:219], v167 offset:4096
	ds_read_b128 v[220:223], v167 offset:5120
	ds_read_b128 v[224:227], v167 offset:6144
	ds_read_b128 v[228:231], v167 offset:7168
	global_load_lds_dwordx4 v[160:161], off
	v_lshl_add_u64 v[160:161], s[22:23], 0, v[154:155]
	s_add_i32 m0, s21, 0xe000
	s_nop 0
	global_load_lds_dwordx4 v[160:161], off
	s_waitcnt vmcnt(8)
	s_waitcnt lgkmcnt(0)
	s_setprio 1
	s_barrier
	v_mfma_f32_16x16x32_bf16 v[124:127], v[128:131], v[184:187], v[124:127]
	v_mfma_f32_16x16x32_bf16 v[120:123], v[136:139], v[184:187], v[120:123]
	v_mfma_f32_16x16x32_bf16 v[116:119], v[128:131], v[198:201], v[116:119]
	v_mfma_f32_16x16x32_bf16 v[112:115], v[136:139], v[198:201], v[112:115]
	v_mfma_f32_16x16x32_bf16 v[108:111], v[128:131], v[216:219], v[108:111]
	v_mfma_f32_16x16x32_bf16 v[100:103], v[136:139], v[216:219], v[100:103]
	v_mfma_f32_16x16x32_bf16 v[80:83], v[128:131], v[224:227], v[80:83]
	v_mfma_f32_16x16x32_bf16 v[72:75], v[136:139], v[224:227], v[72:75]
	v_mfma_f32_16x16x32_bf16 v[124:127], v[132:135], v[188:191], v[124:127]
	v_mfma_f32_16x16x32_bf16 v[120:123], v[140:143], v[188:191], v[120:123]
	v_mfma_f32_16x16x32_bf16 v[116:119], v[132:135], v[202:205], v[116:119]
	v_mfma_f32_16x16x32_bf16 v[112:115], v[140:143], v[202:205], v[112:115]
	v_mfma_f32_16x16x32_bf16 v[108:111], v[132:135], v[220:223], v[108:111]
	v_mfma_f32_16x16x32_bf16 v[100:103], v[140:143], v[220:223], v[100:103]
	v_mfma_f32_16x16x32_bf16 v[80:83], v[132:135], v[228:231], v[80:83]
	v_mfma_f32_16x16x32_bf16 v[72:75], v[140:143], v[228:231], v[72:75]
	v_mfma_f32_16x16x32_bf16 v[104:107], v[168:171], v[184:187], v[104:107]
	v_mfma_f32_16x16x32_bf16 v[96:99], v[176:179], v[184:187], v[96:99]
	v_mfma_f32_16x16x32_bf16 v[92:95], v[168:171], v[198:201], v[92:95]
	v_mfma_f32_16x16x32_bf16 v[88:91], v[176:179], v[198:201], v[88:91]
	v_mfma_f32_16x16x32_bf16 v[84:87], v[168:171], v[216:219], v[84:87]
	v_mfma_f32_16x16x32_bf16 v[76:79], v[176:179], v[216:219], v[76:79]
	v_mfma_f32_16x16x32_bf16 v[68:71], v[168:171], v[224:227], v[68:71]
	v_mfma_f32_16x16x32_bf16 v[64:67], v[176:179], v[224:227], v[64:67]
	v_mfma_f32_16x16x32_bf16 v[104:107], v[172:175], v[188:191], v[104:107]
	v_mfma_f32_16x16x32_bf16 v[96:99], v[180:183], v[188:191], v[96:99]
	v_mfma_f32_16x16x32_bf16 v[92:95], v[172:175], v[202:205], v[92:95]
	v_mfma_f32_16x16x32_bf16 v[88:91], v[180:183], v[202:205], v[88:91]
	v_mfma_f32_16x16x32_bf16 v[84:87], v[172:175], v[220:223], v[84:87]
	v_mfma_f32_16x16x32_bf16 v[76:79], v[180:183], v[220:223], v[76:79]
	s_setprio 0
	v_mfma_f32_16x16x32_bf16 v[68:71], v[172:175], v[228:231], v[68:71]
	v_mfma_f32_16x16x32_bf16 v[64:67], v[180:183], v[228:231], v[64:67]
	s_barrier
	s_add_i32 s52, s40, s29
	v_lshl_add_u64 v[160:161], s[24:25], 0, v[146:147]
	s_mov_b32 m0, s52
	ds_read_b128 v[184:187], v167 offset:16384
	ds_read_b128 v[188:191], v167 offset:17408
	ds_read_b128 v[198:201], v167 offset:18432
	ds_read_b128 v[202:205], v167 offset:19456
	ds_read_b128 v[216:219], v167 offset:20480
	ds_read_b128 v[220:223], v167 offset:21504
	ds_read_b128 v[224:227], v167 offset:22528
	ds_read_b128 v[228:231], v167 offset:23552
	global_load_lds_dwordx4 v[160:161], off
	s_add_i32 m0, s52, 0x2000
	s_add_u32 s52, s24, 0x20000
	v_lshl_add_u64 v[192:193], s[24:25], 0, v[150:151]
	s_addc_u32 s53, s25, 0
	s_add_i32 s54, s41, s29
	global_load_lds_dwordx4 v[192:193], off
	v_lshl_add_u64 v[206:207], s[52:53], 0, v[146:147]
	s_mov_b32 m0, s54
	v_lshl_add_u64 v[210:211], s[26:27], 0, v[148:149]
	global_load_lds_dwordx4 v[206:207], off
	v_lshl_add_u64 v[206:207], s[52:53], 0, v[150:151]
	s_add_i32 m0, s54, 0x2000
	s_nop 0
	global_load_lds_dwordx4 v[206:207], off
	v_lshl_add_u64 v[206:207], s[26:27], 0, v[144:145]
	s_mov_b32 m0, s21
	s_nop 0
	global_load_lds_dwordx4 v[206:207], off
	s_mov_b32 m0, s30
	s_nop 0
	global_load_lds_dwordx4 v[210:211], off
	s_waitcnt vmcnt(8)
	s_waitcnt lgkmcnt(0)
	s_setprio 1
	s_barrier
; #define PG8_STAGE(bufoff, gbase, voff) do { _Pragma("unroll") for (int _i = 0; _i < 2; ++_i) \
;         __builtin_amdgcn_global_load_lds((const unsigned*)((const char*)(gbase) + (voff)[_i]), (LAS unsigned*)(lds + (bufoff) + ldsw + _i * 8192), 16, 0, 0); } while (0)
; #define PG8_LDA(dst, b, h) do { _Pragma("unroll") for (int m = 0; m < 4; ++m) _Pragma("unroll") for (int k = 0; k < 2; ++k) dst[m][k] = *(const LAS bf16x8*)(lds + PG8_SA(b, h) + aoff + m * 2048 + k * 1024); } while (0)
; #define PG8_LDB(dst, b, h) do { _Pragma("unroll") for (int n = 0; n < 2; ++n) _Pragma("unroll") for (int k = 0; k < 2; ++k) dst[n][k] = *(const LAS bf16x8*)(lds + PG8_SB(b, h) + boff + n * 2048 + k * 1024); } while (0)
; #define PG8_MMA(ai, bj, At, Bt) do { __builtin_amdgcn_s_setprio(1); _Pragma("unroll") for (int m = 0; m < 4; ++m) _Pragma("unroll") for (int n = 0; n < 2; ++n) _Pragma("unroll") for (int k = 0; k < 2; ++k) \
;         acc[ai][bj][m][n] = __builtin_amdgcn_mfma_f32_16x16x32_bf16(Bt[n][k], At[m][k], acc[ai][bj][m][n], 0, 0, 0); __builtin_amdgcn_s_setprio(0); } while (0)
; #define PG8_WAIT_V(n) asm volatile("s_waitcnt vmcnt(" #n ")" ::: "memory")
; #define PG8_WAIT_L(n) asm volatile("s_waitcnt lgkmcnt(" #n ")" ::: "memory")
; #define PG8_BAR __builtin_amdgcn_s_barrier()
; #define PG8_SCHED __builtin_amdgcn_sched_barrier(0)
; template <class Epi, bool ALIGN_EPI, bool SP2 = PG8_SP2_DEFAULT>
; __device__ __forceinline__ void gemm_phase(LAS unsigned char* lds, const Gemm g, const StaticOrder& S, const Epi& E) {
;     ...
;             PG8_WAIT_V(8); PG8_WAIT_L(0); PG8_BAR; PG8_MMA(1, 0, At, B0); PG8_MMA(1, 1, At, B1); PG8_BAR; PG8_SCHED;
;             PG8_LDB(B0, 1, 0); PG8_LDB(B1, 1, 1); PG8_SCHED; PG8_LDA(At, 1, 0); PG8_STAGE(PG8_SA(0, 1), a2 + hstepA, voffA);
;             PG8_WAIT_V(8); PG8_WAIT_L(0); PG8_BAR; PG8_MMA(0, 0, At, B0); PG8_MMA(0, 1, At, B1); PG8_BAR; PG8_SCHED;
	v_mfma_f32_16x16x32_bf16 v[60:63], v[128:131], v[184:187], v[60:63]
	v_mfma_f32_16x16x32_bf16 v[56:59], v[136:139], v[184:187], v[56:59]
	v_mfma_f32_16x16x32_bf16 v[52:55], v[128:131], v[198:201], v[52:55]
	v_mfma_f32_16x16x32_bf16 v[44:47], v[136:139], v[198:201], v[44:47]
	v_mfma_f32_16x16x32_bf16 v[36:39], v[128:131], v[216:219], v[36:39]
	v_mfma_f32_16x16x32_bf16 v[28:31], v[136:139], v[216:219], v[28:31]
	v_mfma_f32_16x16x32_bf16 v[20:23], v[128:131], v[224:227], v[20:23]
	v_mfma_f32_16x16x32_bf16 v[12:15], v[136:139], v[224:227], v[12:15]
	v_mfma_f32_16x16x32_bf16 v[60:63], v[132:135], v[188:191], v[60:63]
	v_mfma_f32_16x16x32_bf16 v[56:59], v[140:143], v[188:191], v[56:59]
	v_mfma_f32_16x16x32_bf16 v[52:55], v[132:135], v[202:205], v[52:55]
	v_mfma_f32_16x16x32_bf16 v[44:47], v[140:143], v[202:205], v[44:47]
	v_mfma_f32_16x16x32_bf16 v[36:39], v[132:135], v[220:223], v[36:39]
	v_mfma_f32_16x16x32_bf16 v[28:31], v[140:143], v[220:223], v[28:31]
	v_mfma_f32_16x16x32_bf16 v[20:23], v[132:135], v[228:231], v[20:23]
	v_mfma_f32_16x16x32_bf16 v[12:15], v[140:143], v[228:231], v[12:15]
	v_mfma_f32_16x16x32_bf16 v[48:51], v[168:171], v[184:187], v[48:51]
	v_mfma_f32_16x16x32_bf16 v[40:43], v[176:179], v[184:187], v[40:43]
	v_mfma_f32_16x16x32_bf16 v[32:35], v[168:171], v[198:201], v[32:35]
	v_mfma_f32_16x16x32_bf16 v[24:27], v[176:179], v[198:201], v[24:27]
	v_mfma_f32_16x16x32_bf16 v[16:19], v[168:171], v[216:219], v[16:19]
	v_mfma_f32_16x16x32_bf16 v[8:11], v[176:179], v[216:219], v[8:11]
	v_mfma_f32_16x16x32_bf16 v[4:7], v[168:171], v[224:227], v[4:7]
	v_mfma_f32_16x16x32_bf16 v[0:3], v[176:179], v[224:227], v[0:3]
	v_mfma_f32_16x16x32_bf16 v[48:51], v[172:175], v[188:191], v[48:51]
	v_mfma_f32_16x16x32_bf16 v[40:43], v[180:183], v[188:191], v[40:43]
	v_mfma_f32_16x16x32_bf16 v[32:35], v[172:175], v[202:205], v[32:35]
	v_mfma_f32_16x16x32_bf16 v[24:27], v[180:183], v[202:205], v[24:27]
	v_mfma_f32_16x16x32_bf16 v[16:19], v[172:175], v[220:223], v[16:19]
	v_mfma_f32_16x16x32_bf16 v[8:11], v[180:183], v[220:223], v[8:11]
	s_setprio 0
	v_mfma_f32_16x16x32_bf16 v[4:7], v[172:175], v[228:231], v[4:7]
	v_mfma_f32_16x16x32_bf16 v[0:3], v[180:183], v[228:231], v[0:3]
	s_barrier
	s_add_i32 s52, 0, 0x18000
	s_add_i32 s53, 0, 0x1c000
	v_add_u32_e32 v140, s52, v163
	v_add_u32_e32 v180, s53, v163
	ds_read_b128 v[128:131], v140
	ds_read_b128 v[132:135], v140 offset:1024
	ds_read_b128 v[136:139], v140 offset:2048
	ds_read_b128 v[140:143], v140 offset:3072
	ds_read_b128 v[168:171], v180
	ds_read_b128 v[172:175], v180 offset:1024
	ds_read_b128 v[176:179], v180 offset:2048
	ds_read_b128 v[180:183], v180 offset:3072
	s_add_u32 s26, s26, 0x20000
	s_addc_u32 s27, s27, 0
	s_mov_b32 m0, s31
	v_lshl_add_u64 v[232:233], s[26:27], 0, v[144:145]
	ds_read_b128 v[184:187], v167 offset:32768
	ds_read_b128 v[188:191], v167 offset:33792
	ds_read_b128 v[198:201], v167 offset:34816
	ds_read_b128 v[202:205], v167 offset:35840
	ds_read_b128 v[216:219], v167 offset:36864
	ds_read_b128 v[220:223], v167 offset:37888
	ds_read_b128 v[224:227], v167 offset:38912
	ds_read_b128 v[228:231], v167 offset:39936
	global_load_lds_dwordx4 v[232:233], off
	v_lshl_add_u64 v[232:233], s[26:27], 0, v[148:149]
	s_mov_b32 m0, s34
	s_nop 0
	global_load_lds_dwordx4 v[232:233], off
	s_waitcnt vmcnt(8)
	s_waitcnt lgkmcnt(0)
	s_setprio 1
	s_barrier
	v_mfma_f32_16x16x32_bf16 v[124:127], v[128:131], v[184:187], v[124:127]
	v_mfma_f32_16x16x32_bf16 v[120:123], v[136:139], v[184:187], v[120:123]
	v_mfma_f32_16x16x32_bf16 v[116:119], v[128:131], v[198:201], v[116:119]
	v_mfma_f32_16x16x32_bf16 v[112:115], v[136:139], v[198:201], v[112:115]
	v_mfma_f32_16x16x32_bf16 v[108:111], v[128:131], v[216:219], v[108:111]
	v_mfma_f32_16x16x32_bf16 v[100:103], v[136:139], v[216:219], v[100:103]
	v_mfma_f32_16x16x32_bf16 v[80:83], v[128:131], v[224:227], v[80:83]
	v_mfma_f32_16x16x32_bf16 v[72:75], v[136:139], v[224:227], v[72:75]
	v_mfma_f32_16x16x32_bf16 v[124:127], v[132:135], v[188:191], v[124:127]
	v_mfma_f32_16x16x32_bf16 v[120:123], v[140:143], v[188:191], v[120:123]
	v_mfma_f32_16x16x32_bf16 v[116:119], v[132:135], v[202:205], v[116:119]
	v_mfma_f32_16x16x32_bf16 v[112:115], v[140:143], v[202:205], v[112:115]
	v_mfma_f32_16x16x32_bf16 v[108:111], v[132:135], v[220:223], v[108:111]
	v_mfma_f32_16x16x32_bf16 v[100:103], v[140:143], v[220:223], v[100:103]
	v_mfma_f32_16x16x32_bf16 v[80:83], v[132:135], v[228:231], v[80:83]
	v_mfma_f32_16x16x32_bf16 v[72:75], v[140:143], v[228:231], v[72:75]
	v_mfma_f32_16x16x32_bf16 v[104:107], v[168:171], v[184:187], v[104:107]
	v_mfma_f32_16x16x32_bf16 v[96:99], v[176:179], v[184:187], v[96:99]
	v_mfma_f32_16x16x32_bf16 v[92:95], v[168:171], v[198:201], v[92:95]
	v_mfma_f32_16x16x32_bf16 v[88:91], v[176:179], v[198:201], v[88:91]
	v_mfma_f32_16x16x32_bf16 v[84:87], v[168:171], v[216:219], v[84:87]
	v_mfma_f32_16x16x32_bf16 v[76:79], v[176:179], v[216:219], v[76:79]
	v_mfma_f32_16x16x32_bf16 v[68:71], v[168:171], v[224:227], v[68:71]
	v_mfma_f32_16x16x32_bf16 v[64:67], v[176:179], v[224:227], v[64:67]
	v_mfma_f32_16x16x32_bf16 v[104:107], v[172:175], v[188:191], v[104:107]
	v_mfma_f32_16x16x32_bf16 v[96:99], v[180:183], v[188:191], v[96:99]
	v_mfma_f32_16x16x32_bf16 v[92:95], v[172:175], v[202:205], v[92:95]
	v_mfma_f32_16x16x32_bf16 v[88:91], v[180:183], v[202:205], v[88:91]
	v_mfma_f32_16x16x32_bf16 v[84:87], v[172:175], v[220:223], v[84:87]
	v_mfma_f32_16x16x32_bf16 v[76:79], v[180:183], v[220:223], v[76:79]
	s_setprio 0
	v_mfma_f32_16x16x32_bf16 v[68:71], v[172:175], v[228:231], v[68:71]
	v_mfma_f32_16x16x32_bf16 v[64:67], v[180:183], v[228:231], v[64:67]
	s_barrier
; #define PG8_STAGE(bufoff, gbase, voff) do { _Pragma("unroll") for (int _i = 0; _i < 2; ++_i) \
;         __builtin_amdgcn_global_load_lds((const unsigned*)((const char*)(gbase) + (voff)[_i]), (LAS unsigned*)(lds + (bufoff) + ldsw + _i * 8192), 16, 0, 0); } while (0)
; #define PG8_LDA(dst, b, h) do { _Pragma("unroll") for (int m = 0; m < 4; ++m) _Pragma("unroll") for (int k = 0; k < 2; ++k) dst[m][k] = *(const LAS bf16x8*)(lds + PG8_SA(b, h) + aoff + m * 2048 + k * 1024); } while (0)
; #define PG8_MMA(ai, bj, At, Bt) do { __builtin_amdgcn_s_setprio(1); _Pragma("unroll") for (int m = 0; m < 4; ++m) _Pragma("unroll") for (int n = 0; n < 2; ++n) _Pragma("unroll") for (int k = 0; k < 2; ++k) \
;         acc[ai][bj][m][n] = __builtin_amdgcn_mfma_f32_16x16x32_bf16(Bt[n][k], At[m][k], acc[ai][bj][m][n], 0, 0, 0); __builtin_amdgcn_s_setprio(0); } while (0)
; #define PG8_WAIT_V(n) asm volatile("s_waitcnt vmcnt(" #n ")" ::: "memory")
; #define PG8_WAIT_L(n) asm volatile("s_waitcnt lgkmcnt(" #n ")" ::: "memory")
; #define PG8_BAR __builtin_amdgcn_s_barrier()
; #define PG8_SCHED __builtin_amdgcn_sched_barrier(0)
; template <class Epi, bool ALIGN_EPI, bool SP2 = PG8_SP2_DEFAULT>
; __device__ __forceinline__ void gemm_phase(LAS unsigned char* lds, const Gemm g, const StaticOrder& S, const Epi& E) {
;     ...
;         for (int t = 0; t < nt; t += 2) {
;             const bool last = (t == nt - 2);
;     ...
;             PG8_LDA(At, 1, 1); PG8_STAGE(PG8_SB(1, 0), b3, voffB); PG8_STAGE(PG8_SB(1, 1), b3 + hstepB, voffB); PG8_STAGE(PG8_SA(1, 0), a3, voffA);
;             PG8_WAIT_V(8); PG8_WAIT_L(0); PG8_BAR; PG8_MMA(1, 0, At, B0); PG8_MMA(1, 1, At, B1); PG8_BAR; PG8_SCHED;
	s_add_i32 s26, s52, s29
	v_lshl_add_u64 v[160:161], v[160:161], 0, s[4:5]
	s_mov_b32 m0, s26
	ds_read_b128 v[184:187], v167 offset:49152
	ds_read_b128 v[188:191], v167 offset:50176
	ds_read_b128 v[198:201], v167 offset:51200
	ds_read_b128 v[202:205], v167 offset:52224
	ds_read_b128 v[216:219], v167 offset:53248
	ds_read_b128 v[220:223], v167 offset:54272
	ds_read_b128 v[224:227], v167 offset:55296
	ds_read_b128 v[228:231], v167 offset:56320
	global_load_lds_dwordx4 v[160:161], off
	s_add_i32 m0, s26, 0x2000
	s_add_u32 s24, s24, 0x20080
	v_lshl_add_u64 v[160:161], v[192:193], 0, s[4:5]
	s_addc_u32 s25, s25, 0
	s_add_i32 s26, s53, s29
	global_load_lds_dwordx4 v[160:161], off
	v_lshl_add_u64 v[160:161], s[24:25], 0, v[146:147]
	s_mov_b32 m0, s26
	s_nop 0
	global_load_lds_dwordx4 v[160:161], off
	v_lshl_add_u64 v[160:161], s[24:25], 0, v[150:151]
	s_add_i32 m0, s26, 0x2000
	s_nop 0
	global_load_lds_dwordx4 v[160:161], off
	v_lshl_add_u64 v[160:161], v[206:207], 0, s[4:5]
	s_mov_b32 m0, s36
	s_nop 0
	global_load_lds_dwordx4 v[160:161], off
	v_lshl_add_u64 v[160:161], v[210:211], 0, s[4:5]
	s_mov_b32 m0, s37
	s_nop 0
	global_load_lds_dwordx4 v[160:161], off
	s_waitcnt vmcnt(8)
	s_waitcnt lgkmcnt(0)
	s_setprio 1
	s_barrier
	v_mfma_f32_16x16x32_bf16 v[60:63], v[128:131], v[184:187], v[60:63]
	v_mfma_f32_16x16x32_bf16 v[56:59], v[136:139], v[184:187], v[56:59]
	v_mfma_f32_16x16x32_bf16 v[52:55], v[128:131], v[198:201], v[52:55]
	v_mfma_f32_16x16x32_bf16 v[44:47], v[136:139], v[198:201], v[44:47]
	v_mfma_f32_16x16x32_bf16 v[36:39], v[128:131], v[216:219], v[36:39]
	v_mfma_f32_16x16x32_bf16 v[28:31], v[136:139], v[216:219], v[28:31]
	v_mfma_f32_16x16x32_bf16 v[20:23], v[128:131], v[224:227], v[20:23]
	v_mfma_f32_16x16x32_bf16 v[12:15], v[136:139], v[224:227], v[12:15]
	v_mfma_f32_16x16x32_bf16 v[60:63], v[132:135], v[188:191], v[60:63]
	v_mfma_f32_16x16x32_bf16 v[56:59], v[140:143], v[188:191], v[56:59]
	v_mfma_f32_16x16x32_bf16 v[52:55], v[132:135], v[202:205], v[52:55]
	v_mfma_f32_16x16x32_bf16 v[44:47], v[140:143], v[202:205], v[44:47]
	v_mfma_f32_16x16x32_bf16 v[36:39], v[132:135], v[220:223], v[36:39]
	v_mfma_f32_16x16x32_bf16 v[28:31], v[140:143], v[220:223], v[28:31]
	v_mfma_f32_16x16x32_bf16 v[20:23], v[132:135], v[228:231], v[20:23]
	v_mfma_f32_16x16x32_bf16 v[12:15], v[140:143], v[228:231], v[12:15]
	v_mfma_f32_16x16x32_bf16 v[48:51], v[168:171], v[184:187], v[48:51]
	v_mfma_f32_16x16x32_bf16 v[40:43], v[176:179], v[184:187], v[40:43]
	v_mfma_f32_16x16x32_bf16 v[32:35], v[168:171], v[198:201], v[32:35]
	v_mfma_f32_16x16x32_bf16 v[24:27], v[176:179], v[198:201], v[24:27]
	v_mfma_f32_16x16x32_bf16 v[16:19], v[168:171], v[216:219], v[16:19]
	v_mfma_f32_16x16x32_bf16 v[8:11], v[176:179], v[216:219], v[8:11]
	v_mfma_f32_16x16x32_bf16 v[4:7], v[168:171], v[224:227], v[4:7]
	v_mfma_f32_16x16x32_bf16 v[0:3], v[176:179], v[224:227], v[0:3]
	v_mfma_f32_16x16x32_bf16 v[48:51], v[172:175], v[188:191], v[48:51]
	v_mfma_f32_16x16x32_bf16 v[40:43], v[180:183], v[188:191], v[40:43]
	v_mfma_f32_16x16x32_bf16 v[32:35], v[172:175], v[202:205], v[32:35]
	v_mfma_f32_16x16x32_bf16 v[24:27], v[180:183], v[202:205], v[24:27]
	v_mfma_f32_16x16x32_bf16 v[16:19], v[172:175], v[220:223], v[16:19]
	v_mfma_f32_16x16x32_bf16 v[8:11], v[180:183], v[220:223], v[8:11]
	s_setprio 0
	v_mfma_f32_16x16x32_bf16 v[4:7], v[172:175], v[228:231], v[4:7]
	v_mfma_f32_16x16x32_bf16 v[0:3], v[180:183], v[228:231], v[0:3]
	s_barrier
	s_add_i32 s51, s51, 2
	s_add_u32 s22, s22, 0x100
	s_addc_u32 s23, s23, 0
	s_add_u32 s49, s49, 0x100
	s_addc_u32 s50, s50, 0
	s_cmp_gt_u32 s51, 5
	s_cbranch_scc0 .LBB0_428
	s_and_b64 vcc, exec, s[6:7]
	s_cbranch_vccz .LBB0_431
	s_barrier

; #define PG8_STAGE(bufoff, gbase, voff) do { _Pragma("unroll") for (int _i = 0; _i < 2; ++_i) \
;         __builtin_amdgcn_global_load_lds((const unsigned*)((const char*)(gbase) + (voff)[_i]), (LAS unsigned*)(lds + (bufoff) + ldsw + _i * 8192), 16, 0, 0); } while (0)
; #define PG8_LDA(dst, b, h) do { _Pragma("unroll") for (int m = 0; m < 4; ++m) _Pragma("unroll") for (int k = 0; k < 2; ++k) dst[m][k] = *(const LAS bf16x8*)(lds + PG8_SA(b, h) + aoff + m * 2048 + k * 1024); } while (0)
; #define PG8_LDB(dst, b, h) do { _Pragma("unroll") for (int n = 0; n < 2; ++n) _Pragma("unroll") for (int k = 0; k < 2; ++k) dst[n][k] = *(const LAS bf16x8*)(lds + PG8_SB(b, h) + boff + n * 2048 + k * 1024); } while (0)
; #define PG8_MMA(ai, bj, At, Bt) do { __builtin_amdgcn_s_setprio(1); _Pragma("unroll") for (int m = 0; m < 4; ++m) _Pragma("unroll") for (int n = 0; n < 2; ++n) _Pragma("unroll") for (int k = 0; k < 2; ++k) \
;         acc[ai][bj][m][n] = __builtin_amdgcn_mfma_f32_16x16x32_bf16(Bt[n][k], At[m][k], acc[ai][bj][m][n], 0, 0, 0); __builtin_amdgcn_s_setprio(0); } while (0)
; #define PG8_WAIT_V(n) asm volatile("s_waitcnt vmcnt(" #n ")" ::: "memory")
; #define PG8_WAIT_L(n) asm volatile("s_waitcnt lgkmcnt(" #n ")" ::: "memory")
; #define PG8_BAR __builtin_amdgcn_s_barrier()
; #define PG8_SCHED __builtin_amdgcn_sched_barrier(0)
; template <class Epi, bool ALIGN_EPI, bool SP2 = PG8_SP2_DEFAULT>
; __device__ __forceinline__ void gemm_phase(LAS unsigned char* lds, const Gemm g, const StaticOrder& S, const Epi& E) {
;     ...
;             const bool last = (t == nt - 2);
;             const char* a1 = cA + (size_t)(t + 1) * kstep;
;             const char* a2 = last ? nA : cA + (size_t)(t + 2) * kstep; const char* b2 = last ? nB : cB + (size_t)(t + 2) * kstep;
;             const char* a3 = a2 + kstep; const char* b3 = b2 + kstep;
;             if constexpr (SP2) {
;             PG8_LDB(B0, 0, 0); PG8_LDB(B1, 0, 1); PG8_SCHED; PG8_LDA(At, 0, 0); PG8_STAGE(PG8_SA(1, 1), a1 + hstepA, voffA);
;             PG8_WAIT_V(8); PG8_WAIT_L(0); PG8_BAR; PG8_MMA(0, 0, At, B0); PG8_MMA(0, 1, At, B1); PG8_BAR; PG8_SCHED;
;             PG8_LDA(At, 0, 1); PG8_STAGE(PG8_SB(0, 0), b2, voffB); PG8_STAGE(PG8_SB(0, 1), b2 + hstepB, voffB); PG8_STAGE(PG8_SA(0, 0), a2, voffA);
;             PG8_WAIT_V(8); PG8_WAIT_L(0); PG8_BAR; PG8_MMA(1, 0, At, B0); PG8_MMA(1, 1, At, B1); PG8_BAR; PG8_SCHED;
.LBB0_506:
	ds_read_b128 v[144:147], v151
	ds_read_b128 v[156:159], v151 offset:1024
	ds_read_b128 v[160:163], v151 offset:2048
	ds_read_b128 v[164:167], v151 offset:3072
	ds_read_b128 v[168:171], v152
	ds_read_b128 v[172:175], v152 offset:1024
	ds_read_b128 v[176:179], v152 offset:2048
	ds_read_b128 v[180:183], v152 offset:3072
	s_add_u32 s28, s26, 0xfff00080
	s_addc_u32 s29, s27, -1
	s_cmp_eq_u32 s50, 60
	s_cselect_b32 s31, s19, s29
	s_cselect_b32 s30, s25, s28
	s_cselect_b32 s29, s3, s49
	s_cselect_b32 s28, s47, s48
	v_lshl_add_u64 v[192:193], s[26:27], 0, v[136:137]
	s_add_i32 m0, s34, 0xc000
	ds_read_b128 v[184:187], v153
	ds_read_b128 v[188:191], v153 offset:1024
	ds_read_b128 v[198:201], v153 offset:2048
	ds_read_b128 v[202:205], v153 offset:3072
	ds_read_b128 v[216:219], v153 offset:4096
	ds_read_b128 v[220:223], v153 offset:5120
	ds_read_b128 v[224:227], v153 offset:6144
	ds_read_b128 v[228:231], v153 offset:7168
	global_load_lds_dwordx4 v[192:193], off
	v_lshl_add_u64 v[192:193], s[26:27], 0, v[138:139]
	s_add_i32 m0, s34, 0xe000
	s_nop 0
	global_load_lds_dwordx4 v[192:193], off
	s_waitcnt vmcnt(8)
	s_waitcnt lgkmcnt(0)
	s_setprio 1
	s_barrier
	v_mfma_f32_16x16x32_bf16 v[124:127], v[144:147], v[184:187], v[124:127]
	v_mfma_f32_16x16x32_bf16 v[120:123], v[160:163], v[184:187], v[120:123]
	v_mfma_f32_16x16x32_bf16 v[108:111], v[144:147], v[198:201], v[108:111]
	v_mfma_f32_16x16x32_bf16 v[104:107], v[160:163], v[198:201], v[104:107]
	v_mfma_f32_16x16x32_bf16 v[92:95], v[144:147], v[216:219], v[92:95]
	v_mfma_f32_16x16x32_bf16 v[88:91], v[160:163], v[216:219], v[88:91]
	v_mfma_f32_16x16x32_bf16 v[76:79], v[144:147], v[224:227], v[76:79]
	v_mfma_f32_16x16x32_bf16 v[72:75], v[160:163], v[224:227], v[72:75]
	v_mfma_f32_16x16x32_bf16 v[124:127], v[156:159], v[188:191], v[124:127]
	v_mfma_f32_16x16x32_bf16 v[120:123], v[164:167], v[188:191], v[120:123]
	v_mfma_f32_16x16x32_bf16 v[108:111], v[156:159], v[202:205], v[108:111]
	v_mfma_f32_16x16x32_bf16 v[104:107], v[164:167], v[202:205], v[104:107]
	v_mfma_f32_16x16x32_bf16 v[92:95], v[156:159], v[220:223], v[92:95]
	v_mfma_f32_16x16x32_bf16 v[88:91], v[164:167], v[220:223], v[88:91]
	v_mfma_f32_16x16x32_bf16 v[76:79], v[156:159], v[228:231], v[76:79]
	v_mfma_f32_16x16x32_bf16 v[72:75], v[164:167], v[228:231], v[72:75]
	v_mfma_f32_16x16x32_bf16 v[116:119], v[168:171], v[184:187], v[116:119]
	v_mfma_f32_16x16x32_bf16 v[112:115], v[176:179], v[184:187], v[112:115]
	v_mfma_f32_16x16x32_bf16 v[100:103], v[168:171], v[198:201], v[100:103]
	v_mfma_f32_16x16x32_bf16 v[96:99], v[176:179], v[198:201], v[96:99]
	v_mfma_f32_16x16x32_bf16 v[84:87], v[168:171], v[216:219], v[84:87]
	v_mfma_f32_16x16x32_bf16 v[80:83], v[176:179], v[216:219], v[80:83]
	v_mfma_f32_16x16x32_bf16 v[68:71], v[168:171], v[224:227], v[68:71]
	v_mfma_f32_16x16x32_bf16 v[64:67], v[176:179], v[224:227], v[64:67]
	v_mfma_f32_16x16x32_bf16 v[116:119], v[172:175], v[188:191], v[116:119]
	v_mfma_f32_16x16x32_bf16 v[112:115], v[180:183], v[188:191], v[112:115]
	v_mfma_f32_16x16x32_bf16 v[100:103], v[172:175], v[202:205], v[100:103]
	v_mfma_f32_16x16x32_bf16 v[96:99], v[180:183], v[202:205], v[96:99]
	v_mfma_f32_16x16x32_bf16 v[84:87], v[172:175], v[220:223], v[84:87]
	v_mfma_f32_16x16x32_bf16 v[80:83], v[180:183], v[220:223], v[80:83]
	s_setprio 0
	v_mfma_f32_16x16x32_bf16 v[68:71], v[172:175], v[228:231], v[68:71]
	v_mfma_f32_16x16x32_bf16 v[64:67], v[180:183], v[228:231], v[64:67]
	s_barrier
	s_add_i32 s51, s44, s33
	v_lshl_add_u64 v[192:193], s[28:29], 0, v[130:131]
	s_mov_b32 m0, s51
	ds_read_b128 v[184:187], v153 offset:16384
	ds_read_b128 v[188:191], v153 offset:17408
	ds_read_b128 v[198:201], v153 offset:18432
	ds_read_b128 v[202:205], v153 offset:19456
	ds_read_b128 v[216:219], v153 offset:20480
	ds_read_b128 v[220:223], v153 offset:21504
	ds_read_b128 v[224:227], v153 offset:22528
	ds_read_b128 v[228:231], v153 offset:23552
	global_load_lds_dwordx4 v[192:193], off
	s_add_i32 m0, s51, 0x2000
	s_add_u32 s52, s28, 0x100000
	v_lshl_add_u64 v[206:207], s[28:29], 0, v[134:135]
	s_addc_u32 s53, s29, 0
	s_add_i32 s51, s45, s33
	global_load_lds_dwordx4 v[206:207], off
	v_lshl_add_u64 v[210:211], s[52:53], 0, v[130:131]
	s_mov_b32 m0, s51
	v_lshl_add_u64 v[232:233], s[30:31], 0, v[132:133]
	global_load_lds_dwordx4 v[210:211], off
	v_lshl_add_u64 v[210:211], s[52:53], 0, v[134:135]
	s_add_i32 m0, s51, 0x2000
	s_nop 0
	global_load_lds_dwordx4 v[210:211], off
	v_lshl_add_u64 v[210:211], s[30:31], 0, v[128:129]
	s_mov_b32 m0, s34
	s_nop 0
	global_load_lds_dwordx4 v[210:211], off
	s_mov_b32 m0, s35
	s_nop 0
	global_load_lds_dwordx4 v[232:233], off
	s_waitcnt vmcnt(8)
	s_waitcnt lgkmcnt(0)
	s_setprio 1
	s_barrier
; #define PG8_STAGE(bufoff, gbase, voff) do { _Pragma("unroll") for (int _i = 0; _i < 2; ++_i) \
;         __builtin_amdgcn_global_load_lds((const unsigned*)((const char*)(gbase) + (voff)[_i]), (LAS unsigned*)(lds + (bufoff) + ldsw + _i * 8192), 16, 0, 0); } while (0)
; #define PG8_LDA(dst, b, h) do { _Pragma("unroll") for (int m = 0; m < 4; ++m) _Pragma("unroll") for (int k = 0; k < 2; ++k) dst[m][k] = *(const LAS bf16x8*)(lds + PG8_SA(b, h) + aoff + m * 2048 + k * 1024); } while (0)
; #define PG8_LDB(dst, b, h) do { _Pragma("unroll") for (int n = 0; n < 2; ++n) _Pragma("unroll") for (int k = 0; k < 2; ++k) dst[n][k] = *(const LAS bf16x8*)(lds + PG8_SB(b, h) + boff + n * 2048 + k * 1024); } while (0)
; #define PG8_MMA(ai, bj, At, Bt) do { __builtin_amdgcn_s_setprio(1); _Pragma("unroll") for (int m = 0; m < 4; ++m) _Pragma("unroll") for (int n = 0; n < 2; ++n) _Pragma("unroll") for (int k = 0; k < 2; ++k) \
;         acc[ai][bj][m][n] = __builtin_amdgcn_mfma_f32_16x16x32_bf16(Bt[n][k], At[m][k], acc[ai][bj][m][n], 0, 0, 0); __builtin_amdgcn_s_setprio(0); } while (0)
; #define PG8_WAIT_V(n) asm volatile("s_waitcnt vmcnt(" #n ")" ::: "memory")
; #define PG8_WAIT_L(n) asm volatile("s_waitcnt lgkmcnt(" #n ")" ::: "memory")
; #define PG8_BAR __builtin_amdgcn_s_barrier()
; #define PG8_SCHED __builtin_amdgcn_sched_barrier(0)
; template <class Epi, bool ALIGN_EPI, bool SP2 = PG8_SP2_DEFAULT>
; __device__ __forceinline__ void gemm_phase(LAS unsigned char* lds, const Gemm g, const StaticOrder& S, const Epi& E) {
;     ...
;             PG8_WAIT_V(8); PG8_WAIT_L(0); PG8_BAR; PG8_MMA(1, 0, At, B0); PG8_MMA(1, 1, At, B1); PG8_BAR; PG8_SCHED;
;             PG8_LDB(B0, 1, 0); PG8_LDB(B1, 1, 1); PG8_SCHED; PG8_LDA(At, 1, 0); PG8_STAGE(PG8_SA(0, 1), a2 + hstepA, voffA);
;             PG8_WAIT_V(8); PG8_WAIT_L(0); PG8_BAR; PG8_MMA(0, 0, At, B0); PG8_MMA(0, 1, At, B1); PG8_BAR; PG8_SCHED;
	v_mfma_f32_16x16x32_bf16 v[60:63], v[144:147], v[184:187], v[60:63]
	v_mfma_f32_16x16x32_bf16 v[56:59], v[160:163], v[184:187], v[56:59]
	v_mfma_f32_16x16x32_bf16 v[44:47], v[144:147], v[198:201], v[44:47]
	v_mfma_f32_16x16x32_bf16 v[40:43], v[160:163], v[198:201], v[40:43]
	v_mfma_f32_16x16x32_bf16 v[28:31], v[144:147], v[216:219], v[28:31]
	v_mfma_f32_16x16x32_bf16 v[24:27], v[160:163], v[216:219], v[24:27]
	v_mfma_f32_16x16x32_bf16 v[12:15], v[144:147], v[224:227], v[12:15]
	v_mfma_f32_16x16x32_bf16 v[8:11], v[160:163], v[224:227], v[8:11]
	v_mfma_f32_16x16x32_bf16 v[60:63], v[156:159], v[188:191], v[60:63]
	v_mfma_f32_16x16x32_bf16 v[56:59], v[164:167], v[188:191], v[56:59]
	v_mfma_f32_16x16x32_bf16 v[44:47], v[156:159], v[202:205], v[44:47]
	v_mfma_f32_16x16x32_bf16 v[40:43], v[164:167], v[202:205], v[40:43]
	v_mfma_f32_16x16x32_bf16 v[28:31], v[156:159], v[220:223], v[28:31]
	v_mfma_f32_16x16x32_bf16 v[24:27], v[164:167], v[220:223], v[24:27]
	v_mfma_f32_16x16x32_bf16 v[12:15], v[156:159], v[228:231], v[12:15]
	v_mfma_f32_16x16x32_bf16 v[8:11], v[164:167], v[228:231], v[8:11]
	v_mfma_f32_16x16x32_bf16 v[52:55], v[168:171], v[184:187], v[52:55]
	v_mfma_f32_16x16x32_bf16 v[48:51], v[176:179], v[184:187], v[48:51]
	v_mfma_f32_16x16x32_bf16 v[36:39], v[168:171], v[198:201], v[36:39]
	v_mfma_f32_16x16x32_bf16 v[32:35], v[176:179], v[198:201], v[32:35]
	v_mfma_f32_16x16x32_bf16 v[20:23], v[168:171], v[216:219], v[20:23]
	v_mfma_f32_16x16x32_bf16 v[16:19], v[176:179], v[216:219], v[16:19]
	v_mfma_f32_16x16x32_bf16 v[4:7], v[168:171], v[224:227], v[4:7]
	v_mfma_f32_16x16x32_bf16 v[0:3], v[176:179], v[224:227], v[0:3]
	v_mfma_f32_16x16x32_bf16 v[52:55], v[172:175], v[188:191], v[52:55]
	v_mfma_f32_16x16x32_bf16 v[48:51], v[180:183], v[188:191], v[48:51]
	v_mfma_f32_16x16x32_bf16 v[36:39], v[172:175], v[202:205], v[36:39]
	v_mfma_f32_16x16x32_bf16 v[32:35], v[180:183], v[202:205], v[32:35]
	v_mfma_f32_16x16x32_bf16 v[20:23], v[172:175], v[220:223], v[20:23]
	v_mfma_f32_16x16x32_bf16 v[16:19], v[180:183], v[220:223], v[16:19]
	s_setprio 0
	v_mfma_f32_16x16x32_bf16 v[4:7], v[172:175], v[228:231], v[4:7]
	v_mfma_f32_16x16x32_bf16 v[0:3], v[180:183], v[228:231], v[0:3]
	s_barrier
	s_add_i32 s51, 0, 0x18000
	v_add_u32_e32 v155, s51, v149
	s_add_i32 s52, 0, 0x1c000
	ds_read_b128 v[144:147], v155
	ds_read_b128 v[156:159], v155 offset:1024
	ds_read_b128 v[160:163], v155 offset:2048
	ds_read_b128 v[164:167], v155 offset:3072
	v_add_u32_e32 v155, s52, v149
	ds_read_b128 v[168:171], v155
	ds_read_b128 v[172:175], v155 offset:1024
	ds_read_b128 v[176:179], v155 offset:2048
	ds_read_b128 v[180:183], v155 offset:3072
	s_add_u32 s30, s30, 0x100000
	s_addc_u32 s31, s31, 0
	s_mov_b32 m0, s36
	v_lshl_add_u64 v[234:235], s[30:31], 0, v[128:129]
	ds_read_b128 v[184:187], v153 offset:32768
	ds_read_b128 v[188:191], v153 offset:33792
	ds_read_b128 v[198:201], v153 offset:34816
	ds_read_b128 v[202:205], v153 offset:35840
	ds_read_b128 v[216:219], v153 offset:36864
	ds_read_b128 v[220:223], v153 offset:37888
	ds_read_b128 v[224:227], v153 offset:38912
	ds_read_b128 v[228:231], v153 offset:39936
	global_load_lds_dwordx4 v[234:235], off
	v_lshl_add_u64 v[234:235], s[30:31], 0, v[132:133]
	s_mov_b32 m0, s37
	s_nop 0
	global_load_lds_dwordx4 v[234:235], off
	s_waitcnt vmcnt(8)
	s_waitcnt lgkmcnt(0)
	s_setprio 1
	s_barrier
	v_mfma_f32_16x16x32_bf16 v[124:127], v[144:147], v[184:187], v[124:127]
	v_mfma_f32_16x16x32_bf16 v[120:123], v[160:163], v[184:187], v[120:123]
	v_mfma_f32_16x16x32_bf16 v[108:111], v[144:147], v[198:201], v[108:111]
	v_mfma_f32_16x16x32_bf16 v[104:107], v[160:163], v[198:201], v[104:107]
	v_mfma_f32_16x16x32_bf16 v[92:95], v[144:147], v[216:219], v[92:95]
	v_mfma_f32_16x16x32_bf16 v[88:91], v[160:163], v[216:219], v[88:91]
	v_mfma_f32_16x16x32_bf16 v[76:79], v[144:147], v[224:227], v[76:79]
	v_mfma_f32_16x16x32_bf16 v[72:75], v[160:163], v[224:227], v[72:75]
	v_mfma_f32_16x16x32_bf16 v[124:127], v[156:159], v[188:191], v[124:127]
	v_mfma_f32_16x16x32_bf16 v[120:123], v[164:167], v[188:191], v[120:123]
	v_mfma_f32_16x16x32_bf16 v[108:111], v[156:159], v[202:205], v[108:111]
	v_mfma_f32_16x16x32_bf16 v[104:107], v[164:167], v[202:205], v[104:107]
	v_mfma_f32_16x16x32_bf16 v[92:95], v[156:159], v[220:223], v[92:95]
	v_mfma_f32_16x16x32_bf16 v[88:91], v[164:167], v[220:223], v[88:91]
	v_mfma_f32_16x16x32_bf16 v[76:79], v[156:159], v[228:231], v[76:79]
	v_mfma_f32_16x16x32_bf16 v[72:75], v[164:167], v[228:231], v[72:75]
	v_mfma_f32_16x16x32_bf16 v[116:119], v[168:171], v[184:187], v[116:119]
	v_mfma_f32_16x16x32_bf16 v[112:115], v[176:179], v[184:187], v[112:115]
	v_mfma_f32_16x16x32_bf16 v[100:103], v[168:171], v[198:201], v[100:103]
	v_mfma_f32_16x16x32_bf16 v[96:99], v[176:179], v[198:201], v[96:99]
	v_mfma_f32_16x16x32_bf16 v[84:87], v[168:171], v[216:219], v[84:87]
	v_mfma_f32_16x16x32_bf16 v[80:83], v[176:179], v[216:219], v[80:83]
	v_mfma_f32_16x16x32_bf16 v[68:71], v[168:171], v[224:227], v[68:71]
	v_mfma_f32_16x16x32_bf16 v[64:67], v[176:179], v[224:227], v[64:67]
	v_mfma_f32_16x16x32_bf16 v[116:119], v[172:175], v[188:191], v[116:119]
	v_mfma_f32_16x16x32_bf16 v[112:115], v[180:183], v[188:191], v[112:115]
	v_mfma_f32_16x16x32_bf16 v[100:103], v[172:175], v[202:205], v[100:103]
	v_mfma_f32_16x16x32_bf16 v[96:99], v[180:183], v[202:205], v[96:99]
	v_mfma_f32_16x16x32_bf16 v[84:87], v[172:175], v[220:223], v[84:87]
	v_mfma_f32_16x16x32_bf16 v[80:83], v[180:183], v[220:223], v[80:83]
	s_setprio 0
	v_mfma_f32_16x16x32_bf16 v[68:71], v[172:175], v[228:231], v[68:71]
	v_mfma_f32_16x16x32_bf16 v[64:67], v[180:183], v[228:231], v[64:67]
	s_barrier
; #define PG8_STAGE(bufoff, gbase, voff) do { _Pragma("unroll") for (int _i = 0; _i < 2; ++_i) \
;         __builtin_amdgcn_global_load_lds((const unsigned*)((const char*)(gbase) + (voff)[_i]), (LAS unsigned*)(lds + (bufoff) + ldsw + _i * 8192), 16, 0, 0); } while (0)
; #define PG8_LDA(dst, b, h) do { _Pragma("unroll") for (int m = 0; m < 4; ++m) _Pragma("unroll") for (int k = 0; k < 2; ++k) dst[m][k] = *(const LAS bf16x8*)(lds + PG8_SA(b, h) + aoff + m * 2048 + k * 1024); } while (0)
; #define PG8_MMA(ai, bj, At, Bt) do { __builtin_amdgcn_s_setprio(1); _Pragma("unroll") for (int m = 0; m < 4; ++m) _Pragma("unroll") for (int n = 0; n < 2; ++n) _Pragma("unroll") for (int k = 0; k < 2; ++k) \
;         acc[ai][bj][m][n] = __builtin_amdgcn_mfma_f32_16x16x32_bf16(Bt[n][k], At[m][k], acc[ai][bj][m][n], 0, 0, 0); __builtin_amdgcn_s_setprio(0); } while (0)
; #define PG8_WAIT_V(n) asm volatile("s_waitcnt vmcnt(" #n ")" ::: "memory")
; #define PG8_WAIT_L(n) asm volatile("s_waitcnt lgkmcnt(" #n ")" ::: "memory")
; #define PG8_BAR __builtin_amdgcn_s_barrier()
; #define PG8_SCHED __builtin_amdgcn_sched_barrier(0)
; template <class Epi, bool ALIGN_EPI, bool SP2 = PG8_SP2_DEFAULT>
; __device__ __forceinline__ void gemm_phase(LAS unsigned char* lds, const Gemm g, const StaticOrder& S, const Epi& E) {
;     ...
;         for (int t = 0; t < nt; t += 2) {
;             const bool last = (t == nt - 2);
;     ...
;             PG8_LDA(At, 1, 1); PG8_STAGE(PG8_SB(1, 0), b3, voffB); PG8_STAGE(PG8_SB(1, 1), b3 + hstepB, voffB); PG8_STAGE(PG8_SA(1, 0), a3, voffA);
;             PG8_WAIT_V(8); PG8_WAIT_L(0); PG8_BAR; PG8_MMA(1, 0, At, B0); PG8_MMA(1, 1, At, B1); PG8_BAR; PG8_SCHED;
	s_add_i32 s30, s51, s33
	v_lshl_add_u64 v[192:193], v[192:193], 0, s[14:15]
	s_mov_b32 m0, s30
	ds_read_b128 v[184:187], v153 offset:49152
	ds_read_b128 v[188:191], v153 offset:50176
	ds_read_b128 v[198:201], v153 offset:51200
	ds_read_b128 v[202:205], v153 offset:52224
	ds_read_b128 v[216:219], v153 offset:53248
	ds_read_b128 v[220:223], v153 offset:54272
	ds_read_b128 v[224:227], v153 offset:55296
	ds_read_b128 v[228:231], v153 offset:56320
	global_load_lds_dwordx4 v[192:193], off
	s_add_i32 m0, s30, 0x2000
	s_add_u32 s28, s28, 0x100080
	v_lshl_add_u64 v[192:193], v[206:207], 0, s[14:15]
	s_addc_u32 s29, s29, 0
	s_add_i32 s30, s52, s33
	global_load_lds_dwordx4 v[192:193], off
	v_lshl_add_u64 v[192:193], s[28:29], 0, v[130:131]
	s_mov_b32 m0, s30
	s_nop 0
	global_load_lds_dwordx4 v[192:193], off
	v_lshl_add_u64 v[192:193], s[28:29], 0, v[134:135]
	s_add_i32 m0, s30, 0x2000
	s_nop 0
	global_load_lds_dwordx4 v[192:193], off
	v_lshl_add_u64 v[192:193], v[210:211], 0, s[14:15]
	s_mov_b32 m0, s39
	s_nop 0
	global_load_lds_dwordx4 v[192:193], off
	v_lshl_add_u64 v[192:193], v[232:233], 0, s[14:15]
	s_mov_b32 m0, s40
	s_nop 0
	global_load_lds_dwordx4 v[192:193], off
	s_waitcnt vmcnt(8)
	s_waitcnt lgkmcnt(0)
	s_setprio 1
	s_barrier
	v_mfma_f32_16x16x32_bf16 v[60:63], v[144:147], v[184:187], v[60:63]
	v_mfma_f32_16x16x32_bf16 v[56:59], v[160:163], v[184:187], v[56:59]
	v_mfma_f32_16x16x32_bf16 v[44:47], v[144:147], v[198:201], v[44:47]
	v_mfma_f32_16x16x32_bf16 v[40:43], v[160:163], v[198:201], v[40:43]
	v_mfma_f32_16x16x32_bf16 v[28:31], v[144:147], v[216:219], v[28:31]
	v_mfma_f32_16x16x32_bf16 v[24:27], v[160:163], v[216:219], v[24:27]
	v_mfma_f32_16x16x32_bf16 v[12:15], v[144:147], v[224:227], v[12:15]
	v_mfma_f32_16x16x32_bf16 v[8:11], v[160:163], v[224:227], v[8:11]
	v_mfma_f32_16x16x32_bf16 v[60:63], v[156:159], v[188:191], v[60:63]
	v_mfma_f32_16x16x32_bf16 v[56:59], v[164:167], v[188:191], v[56:59]
	v_mfma_f32_16x16x32_bf16 v[44:47], v[156:159], v[202:205], v[44:47]
	v_mfma_f32_16x16x32_bf16 v[40:43], v[164:167], v[202:205], v[40:43]
	v_mfma_f32_16x16x32_bf16 v[28:31], v[156:159], v[220:223], v[28:31]
	v_mfma_f32_16x16x32_bf16 v[24:27], v[164:167], v[220:223], v[24:27]
	v_mfma_f32_16x16x32_bf16 v[12:15], v[156:159], v[228:231], v[12:15]
	v_mfma_f32_16x16x32_bf16 v[8:11], v[164:167], v[228:231], v[8:11]
	v_mfma_f32_16x16x32_bf16 v[52:55], v[168:171], v[184:187], v[52:55]
	v_mfma_f32_16x16x32_bf16 v[48:51], v[176:179], v[184:187], v[48:51]
	v_mfma_f32_16x16x32_bf16 v[36:39], v[168:171], v[198:201], v[36:39]
	v_mfma_f32_16x16x32_bf16 v[32:35], v[176:179], v[198:201], v[32:35]
	v_mfma_f32_16x16x32_bf16 v[20:23], v[168:171], v[216:219], v[20:23]
	v_mfma_f32_16x16x32_bf16 v[16:19], v[176:179], v[216:219], v[16:19]
	v_mfma_f32_16x16x32_bf16 v[4:7], v[168:171], v[224:227], v[4:7]
	v_mfma_f32_16x16x32_bf16 v[0:3], v[176:179], v[224:227], v[0:3]
	v_mfma_f32_16x16x32_bf16 v[52:55], v[172:175], v[188:191], v[52:55]
	v_mfma_f32_16x16x32_bf16 v[48:51], v[180:183], v[188:191], v[48:51]
	v_mfma_f32_16x16x32_bf16 v[36:39], v[172:175], v[202:205], v[36:39]
	v_mfma_f32_16x16x32_bf16 v[32:35], v[180:183], v[202:205], v[32:35]
	v_mfma_f32_16x16x32_bf16 v[20:23], v[172:175], v[220:223], v[20:23]
	v_mfma_f32_16x16x32_bf16 v[16:19], v[180:183], v[220:223], v[16:19]
	s_setprio 0
	v_mfma_f32_16x16x32_bf16 v[4:7], v[172:175], v[228:231], v[4:7]
	v_mfma_f32_16x16x32_bf16 v[0:3], v[180:183], v[228:231], v[0:3]
	s_barrier
	s_add_i32 s50, s50, 2
	s_add_u32 s26, s26, 0x100
	s_addc_u32 s27, s27, 0
	s_add_u32 s48, s48, 0x100
	s_addc_u32 s49, s49, 0
	s_cmp_gt_u32 s50, 61
	s_cbranch_scc0 .LBB0_506
	s_and_b64 vcc, exec, s[16:17]
	s_cbranch_vccz .LBB0_509
	s_barrier

; #define PG8_STAGE(bufoff, gbase, voff) do { _Pragma("unroll") for (int _i = 0; _i < 2; ++_i) \
;         __builtin_amdgcn_global_load_lds((const unsigned*)((const char*)(gbase) + (voff)[_i]), (LAS unsigned*)(lds + (bufoff) + ldsw + _i * 8192), 16, 0, 0); } while (0)
; #define PG8_LDA(dst, b, h) do { _Pragma("unroll") for (int m = 0; m < 4; ++m) _Pragma("unroll") for (int k = 0; k < 2; ++k) dst[m][k] = *(const LAS bf16x8*)(lds + PG8_SA(b, h) + aoff + m * 2048 + k * 1024); } while (0)
; #define PG8_LDB(dst, b, h) do { _Pragma("unroll") for (int n = 0; n < 2; ++n) _Pragma("unroll") for (int k = 0; k < 2; ++k) dst[n][k] = *(const LAS bf16x8*)(lds + PG8_SB(b, h) + boff + n * 2048 + k * 1024); } while (0)
; #define PG8_MMA(ai, bj, At, Bt) do { __builtin_amdgcn_s_setprio(1); _Pragma("unroll") for (int m = 0; m < 4; ++m) _Pragma("unroll") for (int n = 0; n < 2; ++n) _Pragma("unroll") for (int k = 0; k < 2; ++k) \
;         acc[ai][bj][m][n] = __builtin_amdgcn_mfma_f32_16x16x32_bf16(Bt[n][k], At[m][k], acc[ai][bj][m][n], 0, 0, 0); __builtin_amdgcn_s_setprio(0); } while (0)
; #define PG8_WAIT_V(n) asm volatile("s_waitcnt vmcnt(" #n ")" ::: "memory")
; #define PG8_WAIT_L(n) asm volatile("s_waitcnt lgkmcnt(" #n ")" ::: "memory")
; #define PG8_BAR __builtin_amdgcn_s_barrier()
; #define PG8_SCHED __builtin_amdgcn_sched_barrier(0)
; template <class Epi, bool ALIGN_EPI, bool SP2 = PG8_SP2_DEFAULT>
; __device__ __forceinline__ void gemm_phase(LAS unsigned char* lds, const Gemm g, const StaticOrder& S, const Epi& E) {
;     ...
;             const bool last = (t == nt - 2);
;             const char* a1 = cA + (size_t)(t + 1) * kstep;
;             const char* a2 = last ? nA : cA + (size_t)(t + 2) * kstep; const char* b2 = last ? nB : cB + (size_t)(t + 2) * kstep;
;             const char* a3 = a2 + kstep; const char* b3 = b2 + kstep;
;             if constexpr (SP2) {
;             PG8_LDB(B0, 0, 0); PG8_LDB(B1, 0, 1); PG8_SCHED; PG8_LDA(At, 0, 0); PG8_STAGE(PG8_SA(1, 1), a1 + hstepA, voffA);
;             PG8_WAIT_V(8); PG8_WAIT_L(0); PG8_BAR; PG8_MMA(0, 0, At, B0); PG8_MMA(0, 1, At, B1); PG8_BAR; PG8_SCHED;
;             PG8_LDA(At, 0, 1); PG8_STAGE(PG8_SB(0, 0), b2, voffB); PG8_STAGE(PG8_SB(0, 1), b2 + hstepB, voffB); PG8_STAGE(PG8_SA(0, 0), a2, voffA);
;             PG8_WAIT_V(8); PG8_WAIT_L(0); PG8_BAR; PG8_MMA(1, 0, At, B0); PG8_MMA(1, 1, At, B1); PG8_BAR; PG8_SCHED;
.LBB0_598:
	ds_read_b128 v[146:149], v155
	ds_read_b128 v[160:163], v155 offset:1024
	ds_read_b128 v[164:167], v155 offset:2048
	ds_read_b128 v[168:171], v155 offset:3072
	ds_read_b128 v[172:175], v156
	ds_read_b128 v[176:179], v156 offset:1024
	ds_read_b128 v[180:183], v156 offset:2048
	ds_read_b128 v[184:187], v156 offset:3072
	s_add_u32 s24, s22, 0xfff00080
	s_addc_u32 s25, s23, -1
	s_cmp_eq_u32 s47, 60
	s_cselect_b32 s27, s3, s25
	s_cselect_b32 s26, s7, s24
	s_cselect_b32 s25, s9, s45
	s_cselect_b32 s24, s17, s44
	v_lshl_add_u64 v[192:193], s[22:23], 0, v[138:139]
	s_add_i32 m0, s30, 0xc000
	ds_read_b128 v[188:191], v157
	ds_read_b128 v[198:201], v157 offset:1024
	ds_read_b128 v[202:205], v157 offset:2048
	ds_read_b128 v[214:217], v157 offset:3072
	ds_read_b128 v[218:221], v157 offset:4096
	ds_read_b128 v[222:225], v157 offset:5120
	ds_read_b128 v[226:229], v157 offset:6144
	ds_read_b128 v[230:233], v157 offset:7168
	global_load_lds_dwordx4 v[192:193], off
	v_lshl_add_u64 v[192:193], s[22:23], 0, v[140:141]
	s_add_i32 m0, s30, 0xe000
	s_nop 0
	global_load_lds_dwordx4 v[192:193], off
	s_waitcnt vmcnt(8)
	s_waitcnt lgkmcnt(0)
	s_setprio 1
	s_barrier
	v_mfma_f32_16x16x32_bf16 v[124:127], v[146:149], v[188:191], v[124:127]
	v_mfma_f32_16x16x32_bf16 v[120:123], v[164:167], v[188:191], v[120:123]
	v_mfma_f32_16x16x32_bf16 v[108:111], v[146:149], v[202:205], v[108:111]
	v_mfma_f32_16x16x32_bf16 v[104:107], v[164:167], v[202:205], v[104:107]
	v_mfma_f32_16x16x32_bf16 v[92:95], v[146:149], v[218:221], v[92:95]
	v_mfma_f32_16x16x32_bf16 v[88:91], v[164:167], v[218:221], v[88:91]
	v_mfma_f32_16x16x32_bf16 v[76:79], v[146:149], v[226:229], v[76:79]
	v_mfma_f32_16x16x32_bf16 v[72:75], v[164:167], v[226:229], v[72:75]
	v_mfma_f32_16x16x32_bf16 v[124:127], v[160:163], v[198:201], v[124:127]
	v_mfma_f32_16x16x32_bf16 v[120:123], v[168:171], v[198:201], v[120:123]
	v_mfma_f32_16x16x32_bf16 v[108:111], v[160:163], v[214:217], v[108:111]
	v_mfma_f32_16x16x32_bf16 v[104:107], v[168:171], v[214:217], v[104:107]
	v_mfma_f32_16x16x32_bf16 v[92:95], v[160:163], v[222:225], v[92:95]
	v_mfma_f32_16x16x32_bf16 v[88:91], v[168:171], v[222:225], v[88:91]
	v_mfma_f32_16x16x32_bf16 v[76:79], v[160:163], v[230:233], v[76:79]
	v_mfma_f32_16x16x32_bf16 v[72:75], v[168:171], v[230:233], v[72:75]
	v_mfma_f32_16x16x32_bf16 v[116:119], v[172:175], v[188:191], v[116:119]
	v_mfma_f32_16x16x32_bf16 v[112:115], v[180:183], v[188:191], v[112:115]
	v_mfma_f32_16x16x32_bf16 v[100:103], v[172:175], v[202:205], v[100:103]
	v_mfma_f32_16x16x32_bf16 v[96:99], v[180:183], v[202:205], v[96:99]
	v_mfma_f32_16x16x32_bf16 v[84:87], v[172:175], v[218:221], v[84:87]
	v_mfma_f32_16x16x32_bf16 v[80:83], v[180:183], v[218:221], v[80:83]
	v_mfma_f32_16x16x32_bf16 v[68:71], v[172:175], v[226:229], v[68:71]
	v_mfma_f32_16x16x32_bf16 v[64:67], v[180:183], v[226:229], v[64:67]
	v_mfma_f32_16x16x32_bf16 v[116:119], v[176:179], v[198:201], v[116:119]
	v_mfma_f32_16x16x32_bf16 v[112:115], v[184:187], v[198:201], v[112:115]
	v_mfma_f32_16x16x32_bf16 v[100:103], v[176:179], v[214:217], v[100:103]
	v_mfma_f32_16x16x32_bf16 v[96:99], v[184:187], v[214:217], v[96:99]
	v_mfma_f32_16x16x32_bf16 v[84:87], v[176:179], v[222:225], v[84:87]
	v_mfma_f32_16x16x32_bf16 v[80:83], v[184:187], v[222:225], v[80:83]
	s_setprio 0
	v_mfma_f32_16x16x32_bf16 v[68:71], v[176:179], v[230:233], v[68:71]
	v_mfma_f32_16x16x32_bf16 v[64:67], v[184:187], v[230:233], v[64:67]
	s_barrier
	s_add_i32 s48, s41, s29
	v_lshl_add_u64 v[192:193], s[24:25], 0, v[130:131]
	s_mov_b32 m0, s48
	ds_read_b128 v[188:191], v157 offset:16384
	ds_read_b128 v[198:201], v157 offset:17408
	ds_read_b128 v[202:205], v157 offset:18432
	ds_read_b128 v[214:217], v157 offset:19456
	ds_read_b128 v[218:221], v157 offset:20480
	ds_read_b128 v[222:225], v157 offset:21504
	ds_read_b128 v[226:229], v157 offset:22528
	ds_read_b128 v[230:233], v157 offset:23552
	global_load_lds_dwordx4 v[192:193], off
	s_add_i32 m0, s48, 0x2000
	s_add_u32 s48, s24, 0x100000
	v_lshl_add_u64 v[206:207], s[24:25], 0, v[134:135]
	s_addc_u32 s49, s25, 0
	s_add_i32 s50, s42, s29
	global_load_lds_dwordx4 v[206:207], off
	v_lshl_add_u64 v[210:211], s[48:49], 0, v[130:131]
	s_mov_b32 m0, s50
	v_lshl_add_u64 v[234:235], s[26:27], 0, v[132:133]
	global_load_lds_dwordx4 v[210:211], off
	v_lshl_add_u64 v[210:211], s[48:49], 0, v[134:135]
	s_add_i32 m0, s50, 0x2000
	s_nop 0
	global_load_lds_dwordx4 v[210:211], off
	v_lshl_add_u64 v[210:211], s[26:27], 0, v[128:129]
	s_mov_b32 m0, s30
	s_nop 0
	global_load_lds_dwordx4 v[210:211], off
	s_mov_b32 m0, s31
	s_nop 0
	global_load_lds_dwordx4 v[234:235], off
	s_waitcnt vmcnt(8)
	s_waitcnt lgkmcnt(0)
	s_setprio 1
	s_barrier
; #define PG8_STAGE(bufoff, gbase, voff) do { _Pragma("unroll") for (int _i = 0; _i < 2; ++_i) \
;         __builtin_amdgcn_global_load_lds((const unsigned*)((const char*)(gbase) + (voff)[_i]), (LAS unsigned*)(lds + (bufoff) + ldsw + _i * 8192), 16, 0, 0); } while (0)
; #define PG8_LDA(dst, b, h) do { _Pragma("unroll") for (int m = 0; m < 4; ++m) _Pragma("unroll") for (int k = 0; k < 2; ++k) dst[m][k] = *(const LAS bf16x8*)(lds + PG8_SA(b, h) + aoff + m * 2048 + k * 1024); } while (0)
; #define PG8_LDB(dst, b, h) do { _Pragma("unroll") for (int n = 0; n < 2; ++n) _Pragma("unroll") for (int k = 0; k < 2; ++k) dst[n][k] = *(const LAS bf16x8*)(lds + PG8_SB(b, h) + boff + n * 2048 + k * 1024); } while (0)
; #define PG8_MMA(ai, bj, At, Bt) do { __builtin_amdgcn_s_setprio(1); _Pragma("unroll") for (int m = 0; m < 4; ++m) _Pragma("unroll") for (int n = 0; n < 2; ++n) _Pragma("unroll") for (int k = 0; k < 2; ++k) \
;         acc[ai][bj][m][n] = __builtin_amdgcn_mfma_f32_16x16x32_bf16(Bt[n][k], At[m][k], acc[ai][bj][m][n], 0, 0, 0); __builtin_amdgcn_s_setprio(0); } while (0)
; #define PG8_WAIT_V(n) asm volatile("s_waitcnt vmcnt(" #n ")" ::: "memory")
; #define PG8_WAIT_L(n) asm volatile("s_waitcnt lgkmcnt(" #n ")" ::: "memory")
; #define PG8_BAR __builtin_amdgcn_s_barrier()
; #define PG8_SCHED __builtin_amdgcn_sched_barrier(0)
; template <class Epi, bool ALIGN_EPI, bool SP2 = PG8_SP2_DEFAULT>
; __device__ __forceinline__ void gemm_phase(LAS unsigned char* lds, const Gemm g, const StaticOrder& S, const Epi& E) {
;     ...
;             PG8_WAIT_V(8); PG8_WAIT_L(0); PG8_BAR; PG8_MMA(1, 0, At, B0); PG8_MMA(1, 1, At, B1); PG8_BAR; PG8_SCHED;
;             PG8_LDB(B0, 1, 0); PG8_LDB(B1, 1, 1); PG8_SCHED; PG8_LDA(At, 1, 0); PG8_STAGE(PG8_SA(0, 1), a2 + hstepA, voffA);
;             PG8_WAIT_V(8); PG8_WAIT_L(0); PG8_BAR; PG8_MMA(0, 0, At, B0); PG8_MMA(0, 1, At, B1); PG8_BAR; PG8_SCHED;
	v_mfma_f32_16x16x32_bf16 v[60:63], v[146:149], v[188:191], v[60:63]
	v_mfma_f32_16x16x32_bf16 v[56:59], v[164:167], v[188:191], v[56:59]
	v_mfma_f32_16x16x32_bf16 v[44:47], v[146:149], v[202:205], v[44:47]
	v_mfma_f32_16x16x32_bf16 v[40:43], v[164:167], v[202:205], v[40:43]
	v_mfma_f32_16x16x32_bf16 v[28:31], v[146:149], v[218:221], v[28:31]
	v_mfma_f32_16x16x32_bf16 v[24:27], v[164:167], v[218:221], v[24:27]
	v_mfma_f32_16x16x32_bf16 v[12:15], v[146:149], v[226:229], v[12:15]
	v_mfma_f32_16x16x32_bf16 v[8:11], v[164:167], v[226:229], v[8:11]
	v_mfma_f32_16x16x32_bf16 v[60:63], v[160:163], v[198:201], v[60:63]
	v_mfma_f32_16x16x32_bf16 v[56:59], v[168:171], v[198:201], v[56:59]
	v_mfma_f32_16x16x32_bf16 v[44:47], v[160:163], v[214:217], v[44:47]
	v_mfma_f32_16x16x32_bf16 v[40:43], v[168:171], v[214:217], v[40:43]
	v_mfma_f32_16x16x32_bf16 v[28:31], v[160:163], v[222:225], v[28:31]
	v_mfma_f32_16x16x32_bf16 v[24:27], v[168:171], v[222:225], v[24:27]
	v_mfma_f32_16x16x32_bf16 v[12:15], v[160:163], v[230:233], v[12:15]
	v_mfma_f32_16x16x32_bf16 v[8:11], v[168:171], v[230:233], v[8:11]
	v_mfma_f32_16x16x32_bf16 v[52:55], v[172:175], v[188:191], v[52:55]
	v_mfma_f32_16x16x32_bf16 v[48:51], v[180:183], v[188:191], v[48:51]
	v_mfma_f32_16x16x32_bf16 v[36:39], v[172:175], v[202:205], v[36:39]
	v_mfma_f32_16x16x32_bf16 v[32:35], v[180:183], v[202:205], v[32:35]
	v_mfma_f32_16x16x32_bf16 v[20:23], v[172:175], v[218:221], v[20:23]
	v_mfma_f32_16x16x32_bf16 v[16:19], v[180:183], v[218:221], v[16:19]
	v_mfma_f32_16x16x32_bf16 v[4:7], v[172:175], v[226:229], v[4:7]
	v_mfma_f32_16x16x32_bf16 v[0:3], v[180:183], v[226:229], v[0:3]
	v_mfma_f32_16x16x32_bf16 v[52:55], v[176:179], v[198:201], v[52:55]
	v_mfma_f32_16x16x32_bf16 v[48:51], v[184:187], v[198:201], v[48:51]
	v_mfma_f32_16x16x32_bf16 v[36:39], v[176:179], v[214:217], v[36:39]
	v_mfma_f32_16x16x32_bf16 v[32:35], v[184:187], v[214:217], v[32:35]
	v_mfma_f32_16x16x32_bf16 v[20:23], v[176:179], v[222:225], v[20:23]
	v_mfma_f32_16x16x32_bf16 v[16:19], v[184:187], v[222:225], v[16:19]
	s_setprio 0
	v_mfma_f32_16x16x32_bf16 v[4:7], v[176:179], v[230:233], v[4:7]
	v_mfma_f32_16x16x32_bf16 v[0:3], v[184:187], v[230:233], v[0:3]
	s_barrier
	s_add_i32 s48, 0, 0x18000
	v_add_u32_e32 v150, s48, v152
	s_add_i32 s49, 0, 0x1c000
	ds_read_b128 v[146:149], v150
	ds_read_b128 v[160:163], v150 offset:1024
	ds_read_b128 v[164:167], v150 offset:2048
	ds_read_b128 v[168:171], v150 offset:3072
	v_add_u32_e32 v150, s49, v152
	ds_read_b128 v[172:175], v150
	ds_read_b128 v[176:179], v150 offset:1024
	ds_read_b128 v[180:183], v150 offset:2048
	ds_read_b128 v[184:187], v150 offset:3072
	s_add_u32 s26, s26, 0x100000
	s_addc_u32 s27, s27, 0
	s_mov_b32 m0, s33
	v_lshl_add_u64 v[236:237], s[26:27], 0, v[128:129]
	ds_read_b128 v[188:191], v157 offset:32768
	ds_read_b128 v[198:201], v157 offset:33792
	ds_read_b128 v[202:205], v157 offset:34816
	ds_read_b128 v[214:217], v157 offset:35840
	ds_read_b128 v[218:221], v157 offset:36864
	ds_read_b128 v[222:225], v157 offset:37888
	ds_read_b128 v[226:229], v157 offset:38912
	ds_read_b128 v[230:233], v157 offset:39936
	global_load_lds_dwordx4 v[236:237], off
	v_lshl_add_u64 v[236:237], s[26:27], 0, v[132:133]
	s_mov_b32 m0, s34
	s_nop 0
	global_load_lds_dwordx4 v[236:237], off
	s_waitcnt vmcnt(8)
	s_waitcnt lgkmcnt(0)
	s_setprio 1
	s_barrier
	v_mfma_f32_16x16x32_bf16 v[124:127], v[146:149], v[188:191], v[124:127]
	v_mfma_f32_16x16x32_bf16 v[120:123], v[164:167], v[188:191], v[120:123]
	v_mfma_f32_16x16x32_bf16 v[108:111], v[146:149], v[202:205], v[108:111]
	v_mfma_f32_16x16x32_bf16 v[104:107], v[164:167], v[202:205], v[104:107]
	v_mfma_f32_16x16x32_bf16 v[92:95], v[146:149], v[218:221], v[92:95]
	v_mfma_f32_16x16x32_bf16 v[88:91], v[164:167], v[218:221], v[88:91]
	v_mfma_f32_16x16x32_bf16 v[76:79], v[146:149], v[226:229], v[76:79]
	v_mfma_f32_16x16x32_bf16 v[72:75], v[164:167], v[226:229], v[72:75]
	v_mfma_f32_16x16x32_bf16 v[124:127], v[160:163], v[198:201], v[124:127]
	v_mfma_f32_16x16x32_bf16 v[120:123], v[168:171], v[198:201], v[120:123]
	v_mfma_f32_16x16x32_bf16 v[108:111], v[160:163], v[214:217], v[108:111]
	v_mfma_f32_16x16x32_bf16 v[104:107], v[168:171], v[214:217], v[104:107]
	v_mfma_f32_16x16x32_bf16 v[92:95], v[160:163], v[222:225], v[92:95]
	v_mfma_f32_16x16x32_bf16 v[88:91], v[168:171], v[222:225], v[88:91]
	v_mfma_f32_16x16x32_bf16 v[76:79], v[160:163], v[230:233], v[76:79]
	v_mfma_f32_16x16x32_bf16 v[72:75], v[168:171], v[230:233], v[72:75]
	v_mfma_f32_16x16x32_bf16 v[116:119], v[172:175], v[188:191], v[116:119]
	v_mfma_f32_16x16x32_bf16 v[112:115], v[180:183], v[188:191], v[112:115]
	v_mfma_f32_16x16x32_bf16 v[100:103], v[172:175], v[202:205], v[100:103]
	v_mfma_f32_16x16x32_bf16 v[96:99], v[180:183], v[202:205], v[96:99]
	v_mfma_f32_16x16x32_bf16 v[84:87], v[172:175], v[218:221], v[84:87]
	v_mfma_f32_16x16x32_bf16 v[80:83], v[180:183], v[218:221], v[80:83]
	v_mfma_f32_16x16x32_bf16 v[68:71], v[172:175], v[226:229], v[68:71]
	v_mfma_f32_16x16x32_bf16 v[64:67], v[180:183], v[226:229], v[64:67]
	v_mfma_f32_16x16x32_bf16 v[116:119], v[176:179], v[198:201], v[116:119]
	v_mfma_f32_16x16x32_bf16 v[112:115], v[184:187], v[198:201], v[112:115]
	v_mfma_f32_16x16x32_bf16 v[100:103], v[176:179], v[214:217], v[100:103]
	v_mfma_f32_16x16x32_bf16 v[96:99], v[184:187], v[214:217], v[96:99]
	v_mfma_f32_16x16x32_bf16 v[84:87], v[176:179], v[222:225], v[84:87]
	v_mfma_f32_16x16x32_bf16 v[80:83], v[184:187], v[222:225], v[80:83]
	s_setprio 0
	v_mfma_f32_16x16x32_bf16 v[68:71], v[176:179], v[230:233], v[68:71]
	v_mfma_f32_16x16x32_bf16 v[64:67], v[184:187], v[230:233], v[64:67]
	s_barrier
; #define PG8_STAGE(bufoff, gbase, voff) do { _Pragma("unroll") for (int _i = 0; _i < 2; ++_i) \
;         __builtin_amdgcn_global_load_lds((const unsigned*)((const char*)(gbase) + (voff)[_i]), (LAS unsigned*)(lds + (bufoff) + ldsw + _i * 8192), 16, 0, 0); } while (0)
; #define PG8_LDA(dst, b, h) do { _Pragma("unroll") for (int m = 0; m < 4; ++m) _Pragma("unroll") for (int k = 0; k < 2; ++k) dst[m][k] = *(const LAS bf16x8*)(lds + PG8_SA(b, h) + aoff + m * 2048 + k * 1024); } while (0)
; #define PG8_MMA(ai, bj, At, Bt) do { __builtin_amdgcn_s_setprio(1); _Pragma("unroll") for (int m = 0; m < 4; ++m) _Pragma("unroll") for (int n = 0; n < 2; ++n) _Pragma("unroll") for (int k = 0; k < 2; ++k) \
;         acc[ai][bj][m][n] = __builtin_amdgcn_mfma_f32_16x16x32_bf16(Bt[n][k], At[m][k], acc[ai][bj][m][n], 0, 0, 0); __builtin_amdgcn_s_setprio(0); } while (0)
; #define PG8_WAIT_V(n) asm volatile("s_waitcnt vmcnt(" #n ")" ::: "memory")
; #define PG8_WAIT_L(n) asm volatile("s_waitcnt lgkmcnt(" #n ")" ::: "memory")
; #define PG8_BAR __builtin_amdgcn_s_barrier()
; #define PG8_SCHED __builtin_amdgcn_sched_barrier(0)
; template <class Epi, bool ALIGN_EPI, bool SP2 = PG8_SP2_DEFAULT>
; __device__ __forceinline__ void gemm_phase(LAS unsigned char* lds, const Gemm g, const StaticOrder& S, const Epi& E) {
;     ...
;         for (int t = 0; t < nt; t += 2) {
;             const bool last = (t == nt - 2);
;     ...
;             PG8_LDA(At, 1, 1); PG8_STAGE(PG8_SB(1, 0), b3, voffB); PG8_STAGE(PG8_SB(1, 1), b3 + hstepB, voffB); PG8_STAGE(PG8_SA(1, 0), a3, voffA);
;             PG8_WAIT_V(8); PG8_WAIT_L(0); PG8_BAR; PG8_MMA(1, 0, At, B0); PG8_MMA(1, 1, At, B1); PG8_BAR; PG8_SCHED;
	s_add_i32 s26, s48, s29
	v_lshl_add_u64 v[192:193], v[192:193], 0, s[12:13]
	s_mov_b32 m0, s26
	ds_read_b128 v[188:191], v157 offset:49152
	ds_read_b128 v[198:201], v157 offset:50176
	ds_read_b128 v[202:205], v157 offset:51200
	ds_read_b128 v[214:217], v157 offset:52224
	ds_read_b128 v[218:221], v157 offset:53248
	ds_read_b128 v[222:225], v157 offset:54272
	ds_read_b128 v[226:229], v157 offset:55296
	ds_read_b128 v[230:233], v157 offset:56320
	global_load_lds_dwordx4 v[192:193], off
	s_add_i32 m0, s26, 0x2000
	s_add_u32 s24, s24, 0x100080
	v_lshl_add_u64 v[192:193], v[206:207], 0, s[12:13]
	s_addc_u32 s25, s25, 0
	s_add_i32 s26, s49, s29
	global_load_lds_dwordx4 v[192:193], off
	v_lshl_add_u64 v[192:193], s[24:25], 0, v[130:131]
	s_mov_b32 m0, s26
	s_nop 0
	global_load_lds_dwordx4 v[192:193], off
	v_lshl_add_u64 v[192:193], s[24:25], 0, v[134:135]
	s_add_i32 m0, s26, 0x2000
	s_nop 0
	global_load_lds_dwordx4 v[192:193], off
	v_lshl_add_u64 v[192:193], v[210:211], 0, s[12:13]
	s_mov_b32 m0, s36
	s_nop 0
	global_load_lds_dwordx4 v[192:193], off
	v_lshl_add_u64 v[192:193], v[234:235], 0, s[12:13]
	s_mov_b32 m0, s37
	s_nop 0
	global_load_lds_dwordx4 v[192:193], off
	s_waitcnt vmcnt(8)
	s_waitcnt lgkmcnt(0)
	s_setprio 1
	s_barrier
	v_mfma_f32_16x16x32_bf16 v[60:63], v[146:149], v[188:191], v[60:63]
	v_mfma_f32_16x16x32_bf16 v[56:59], v[164:167], v[188:191], v[56:59]
	v_mfma_f32_16x16x32_bf16 v[44:47], v[146:149], v[202:205], v[44:47]
	v_mfma_f32_16x16x32_bf16 v[40:43], v[164:167], v[202:205], v[40:43]
	v_mfma_f32_16x16x32_bf16 v[28:31], v[146:149], v[218:221], v[28:31]
	v_mfma_f32_16x16x32_bf16 v[24:27], v[164:167], v[218:221], v[24:27]
	v_mfma_f32_16x16x32_bf16 v[12:15], v[146:149], v[226:229], v[12:15]
	v_mfma_f32_16x16x32_bf16 v[8:11], v[164:167], v[226:229], v[8:11]
	v_mfma_f32_16x16x32_bf16 v[60:63], v[160:163], v[198:201], v[60:63]
	v_mfma_f32_16x16x32_bf16 v[56:59], v[168:171], v[198:201], v[56:59]
	v_mfma_f32_16x16x32_bf16 v[44:47], v[160:163], v[214:217], v[44:47]
	v_mfma_f32_16x16x32_bf16 v[40:43], v[168:171], v[214:217], v[40:43]
	v_mfma_f32_16x16x32_bf16 v[28:31], v[160:163], v[222:225], v[28:31]
	v_mfma_f32_16x16x32_bf16 v[24:27], v[168:171], v[222:225], v[24:27]
	v_mfma_f32_16x16x32_bf16 v[12:15], v[160:163], v[230:233], v[12:15]
	v_mfma_f32_16x16x32_bf16 v[8:11], v[168:171], v[230:233], v[8:11]
	v_mfma_f32_16x16x32_bf16 v[52:55], v[172:175], v[188:191], v[52:55]
	v_mfma_f32_16x16x32_bf16 v[48:51], v[180:183], v[188:191], v[48:51]
	v_mfma_f32_16x16x32_bf16 v[36:39], v[172:175], v[202:205], v[36:39]
	v_mfma_f32_16x16x32_bf16 v[32:35], v[180:183], v[202:205], v[32:35]
	v_mfma_f32_16x16x32_bf16 v[20:23], v[172:175], v[218:221], v[20:23]
	v_mfma_f32_16x16x32_bf16 v[16:19], v[180:183], v[218:221], v[16:19]
	v_mfma_f32_16x16x32_bf16 v[4:7], v[172:175], v[226:229], v[4:7]
	v_mfma_f32_16x16x32_bf16 v[0:3], v[180:183], v[226:229], v[0:3]
	v_mfma_f32_16x16x32_bf16 v[52:55], v[176:179], v[198:201], v[52:55]
	v_mfma_f32_16x16x32_bf16 v[48:51], v[184:187], v[198:201], v[48:51]
	v_mfma_f32_16x16x32_bf16 v[36:39], v[176:179], v[214:217], v[36:39]
	v_mfma_f32_16x16x32_bf16 v[32:35], v[184:187], v[214:217], v[32:35]
	v_mfma_f32_16x16x32_bf16 v[20:23], v[176:179], v[222:225], v[20:23]
	v_mfma_f32_16x16x32_bf16 v[16:19], v[184:187], v[222:225], v[16:19]
	s_setprio 0
	v_mfma_f32_16x16x32_bf16 v[4:7], v[176:179], v[230:233], v[4:7]
	v_mfma_f32_16x16x32_bf16 v[0:3], v[184:187], v[230:233], v[0:3]
	s_barrier
	s_add_i32 s47, s47, 2
	s_add_u32 s22, s22, 0x100
	s_addc_u32 s23, s23, 0
	s_add_u32 s44, s44, 0x100
	s_addc_u32 s45, s45, 0
	s_cmp_gt_u32 s47, 61
	s_cbranch_scc0 .LBB0_598
	s_and_b64 vcc, exec, s[14:15]
	s_cbranch_vccz .LBB0_601
	s_barrier

; #define PG8_STAGE(bufoff, gbase, voff) do { _Pragma("unroll") for (int _i = 0; _i < 2; ++_i) \
;         __builtin_amdgcn_global_load_lds((const unsigned*)((const char*)(gbase) + (voff)[_i]), (LAS unsigned*)(lds + (bufoff) + ldsw + _i * 8192), 16, 0, 0); } while (0)
; #define PG8_LDA(dst, b, h) do { _Pragma("unroll") for (int m = 0; m < 4; ++m) _Pragma("unroll") for (int k = 0; k < 2; ++k) dst[m][k] = *(const LAS bf16x8*)(lds + PG8_SA(b, h) + aoff + m * 2048 + k * 1024); } while (0)
; #define PG8_LDB(dst, b, h) do { _Pragma("unroll") for (int n = 0; n < 2; ++n) _Pragma("unroll") for (int k = 0; k < 2; ++k) dst[n][k] = *(const LAS bf16x8*)(lds + PG8_SB(b, h) + boff + n * 2048 + k * 1024); } while (0)
; #define PG8_MMA(ai, bj, At, Bt) do { __builtin_amdgcn_s_setprio(1); _Pragma("unroll") for (int m = 0; m < 4; ++m) _Pragma("unroll") for (int n = 0; n < 2; ++n) _Pragma("unroll") for (int k = 0; k < 2; ++k) \
;         acc[ai][bj][m][n] = __builtin_amdgcn_mfma_f32_16x16x32_bf16(Bt[n][k], At[m][k], acc[ai][bj][m][n], 0, 0, 0); __builtin_amdgcn_s_setprio(0); } while (0)
; #define PG8_WAIT_V(n) asm volatile("s_waitcnt vmcnt(" #n ")" ::: "memory")
; #define PG8_WAIT_L(n) asm volatile("s_waitcnt lgkmcnt(" #n ")" ::: "memory")
; #define PG8_BAR __builtin_amdgcn_s_barrier()
; #define PG8_SCHED __builtin_amdgcn_sched_barrier(0)
; template <class Epi, bool ALIGN_EPI, bool SP2 = PG8_SP2_DEFAULT>
; __device__ __forceinline__ void gemm_phase(LAS unsigned char* lds, const Gemm g, const StaticOrder& S, const Epi& E) {
;     ...
;             const bool last = (t == nt - 2);
;             const char* a1 = cA + (size_t)(t + 1) * kstep;
;             const char* a2 = last ? nA : cA + (size_t)(t + 2) * kstep; const char* b2 = last ? nB : cB + (size_t)(t + 2) * kstep;
;             const char* a3 = a2 + kstep; const char* b3 = b2 + kstep;
;             if constexpr (SP2) {
;             PG8_LDB(B0, 0, 0); PG8_LDB(B1, 0, 1); PG8_SCHED; PG8_LDA(At, 0, 0); PG8_STAGE(PG8_SA(1, 1), a1 + hstepA, voffA);
;             PG8_WAIT_V(8); PG8_WAIT_L(0); PG8_BAR; PG8_MMA(0, 0, At, B0); PG8_MMA(0, 1, At, B1); PG8_BAR; PG8_SCHED;
;             PG8_LDA(At, 0, 1); PG8_STAGE(PG8_SB(0, 0), b2, voffB); PG8_STAGE(PG8_SB(0, 1), b2 + hstepB, voffB); PG8_STAGE(PG8_SA(0, 0), a2, voffA);
;             PG8_WAIT_V(8); PG8_WAIT_L(0); PG8_BAR; PG8_MMA(1, 0, At, B0); PG8_MMA(1, 1, At, B1); PG8_BAR; PG8_SCHED;
.LBB0_804:
	ds_read_b128 v[144:147], v153
	ds_read_b128 v[156:159], v153 offset:1024
	ds_read_b128 v[160:163], v153 offset:2048
	ds_read_b128 v[164:167], v153 offset:3072
	ds_read_b128 v[168:171], v154
	ds_read_b128 v[172:175], v154 offset:1024
	ds_read_b128 v[176:179], v154 offset:2048
	ds_read_b128 v[180:183], v154 offset:3072
	s_add_u32 s22, s20, 0x100
	s_addc_u32 s23, s21, 0
	s_cmpk_eq_i32 s49, 0xa8
	s_cselect_b32 s27, s5, s23
	s_cselect_b32 s26, s4, s22
	s_cselect_b32 s25, s19, s48
	s_cselect_b32 s24, s18, s47
	v_lshl_add_u64 v[148:149], s[20:21], 0, v[136:137]
	s_add_i32 m0, s31, 0xc000
	ds_read_b128 v[184:187], v155
	ds_read_b128 v[188:191], v155 offset:1024
	ds_read_b128 v[192:195], v155 offset:2048
	ds_read_b128 v[196:199], v155 offset:3072
	ds_read_b128 v[200:203], v155 offset:4096
	ds_read_b128 v[204:207], v155 offset:5120
	ds_read_b128 v[208:211], v155 offset:6144
	ds_read_b128 v[212:215], v155 offset:7168
	global_load_lds_dwordx4 v[148:149], off
	v_lshl_add_u64 v[148:149], s[20:21], 0, v[138:139]
	s_add_i32 m0, s31, 0xe000
	s_nop 0
	global_load_lds_dwordx4 v[148:149], off
	s_waitcnt vmcnt(8)
	s_waitcnt lgkmcnt(0)
	s_setprio 1
	s_barrier
	v_mfma_f32_16x16x32_bf16 v[124:127], v[144:147], v[184:187], v[124:127]
	v_mfma_f32_16x16x32_bf16 v[120:123], v[160:163], v[184:187], v[120:123]
	v_mfma_f32_16x16x32_bf16 v[108:111], v[144:147], v[192:195], v[108:111]
	v_mfma_f32_16x16x32_bf16 v[104:107], v[160:163], v[192:195], v[104:107]
	v_mfma_f32_16x16x32_bf16 v[92:95], v[144:147], v[200:203], v[92:95]
	v_mfma_f32_16x16x32_bf16 v[88:91], v[160:163], v[200:203], v[88:91]
	v_mfma_f32_16x16x32_bf16 v[76:79], v[144:147], v[208:211], v[76:79]
	v_mfma_f32_16x16x32_bf16 v[72:75], v[160:163], v[208:211], v[72:75]
	v_mfma_f32_16x16x32_bf16 v[124:127], v[156:159], v[188:191], v[124:127]
	v_mfma_f32_16x16x32_bf16 v[120:123], v[164:167], v[188:191], v[120:123]
	v_mfma_f32_16x16x32_bf16 v[108:111], v[156:159], v[196:199], v[108:111]
	v_mfma_f32_16x16x32_bf16 v[104:107], v[164:167], v[196:199], v[104:107]
	v_mfma_f32_16x16x32_bf16 v[92:95], v[156:159], v[204:207], v[92:95]
	v_mfma_f32_16x16x32_bf16 v[88:91], v[164:167], v[204:207], v[88:91]
	v_mfma_f32_16x16x32_bf16 v[76:79], v[156:159], v[212:215], v[76:79]
	v_mfma_f32_16x16x32_bf16 v[72:75], v[164:167], v[212:215], v[72:75]
	v_mfma_f32_16x16x32_bf16 v[116:119], v[168:171], v[184:187], v[116:119]
	v_mfma_f32_16x16x32_bf16 v[112:115], v[176:179], v[184:187], v[112:115]
	v_mfma_f32_16x16x32_bf16 v[100:103], v[168:171], v[192:195], v[100:103]
	v_mfma_f32_16x16x32_bf16 v[96:99], v[176:179], v[192:195], v[96:99]
	v_mfma_f32_16x16x32_bf16 v[84:87], v[168:171], v[200:203], v[84:87]
	v_mfma_f32_16x16x32_bf16 v[80:83], v[176:179], v[200:203], v[80:83]
	v_mfma_f32_16x16x32_bf16 v[68:71], v[168:171], v[208:211], v[68:71]
	v_mfma_f32_16x16x32_bf16 v[64:67], v[176:179], v[208:211], v[64:67]
	v_mfma_f32_16x16x32_bf16 v[116:119], v[172:175], v[188:191], v[116:119]
	v_mfma_f32_16x16x32_bf16 v[112:115], v[180:183], v[188:191], v[112:115]
	v_mfma_f32_16x16x32_bf16 v[100:103], v[172:175], v[196:199], v[100:103]
	v_mfma_f32_16x16x32_bf16 v[96:99], v[180:183], v[196:199], v[96:99]
	v_mfma_f32_16x16x32_bf16 v[84:87], v[172:175], v[204:207], v[84:87]
	v_mfma_f32_16x16x32_bf16 v[80:83], v[180:183], v[204:207], v[80:83]
	s_setprio 0
	v_mfma_f32_16x16x32_bf16 v[68:71], v[172:175], v[212:215], v[68:71]
	v_mfma_f32_16x16x32_bf16 v[64:67], v[180:183], v[212:215], v[64:67]
	s_barrier
	s_add_i32 s20, s40, s28
	v_lshl_add_u64 v[148:149], s[24:25], 0, v[130:131]
	s_mov_b32 m0, s20
	ds_read_b128 v[184:187], v155 offset:16384
	ds_read_b128 v[188:191], v155 offset:17408
	ds_read_b128 v[192:195], v155 offset:18432
	ds_read_b128 v[196:199], v155 offset:19456
	ds_read_b128 v[200:203], v155 offset:20480
	ds_read_b128 v[204:207], v155 offset:21504
	ds_read_b128 v[208:211], v155 offset:22528
	ds_read_b128 v[212:215], v155 offset:23552
	global_load_lds_dwordx4 v[148:149], off
	s_add_i32 m0, s20, 0x2000
	s_add_u32 s20, s24, 0x2b0000
	v_lshl_add_u64 v[216:217], s[24:25], 0, v[134:135]
	s_addc_u32 s21, s25, 0
	s_add_i32 s50, s41, s28
	global_load_lds_dwordx4 v[216:217], off
	v_lshl_add_u64 v[218:219], s[20:21], 0, v[130:131]
	s_mov_b32 m0, s50
	v_lshl_add_u64 v[220:221], s[26:27], 0, v[132:133]
	global_load_lds_dwordx4 v[218:219], off
	v_lshl_add_u64 v[218:219], s[20:21], 0, v[134:135]
	s_add_i32 m0, s50, 0x2000
	s_nop 0
	global_load_lds_dwordx4 v[218:219], off
	v_lshl_add_u64 v[218:219], s[26:27], 0, v[128:129]
	s_mov_b32 m0, s31
	s_nop 0
	global_load_lds_dwordx4 v[218:219], off
	s_mov_b32 m0, s33
	s_nop 0
	global_load_lds_dwordx4 v[220:221], off
	s_waitcnt vmcnt(8)
	s_waitcnt lgkmcnt(0)
	s_setprio 1
	s_barrier
; #define PG8_STAGE(bufoff, gbase, voff) do { _Pragma("unroll") for (int _i = 0; _i < 2; ++_i) \
;         __builtin_amdgcn_global_load_lds((const unsigned*)((const char*)(gbase) + (voff)[_i]), (LAS unsigned*)(lds + (bufoff) + ldsw + _i * 8192), 16, 0, 0); } while (0)
; #define PG8_LDA(dst, b, h) do { _Pragma("unroll") for (int m = 0; m < 4; ++m) _Pragma("unroll") for (int k = 0; k < 2; ++k) dst[m][k] = *(const LAS bf16x8*)(lds + PG8_SA(b, h) + aoff + m * 2048 + k * 1024); } while (0)
; #define PG8_LDB(dst, b, h) do { _Pragma("unroll") for (int n = 0; n < 2; ++n) _Pragma("unroll") for (int k = 0; k < 2; ++k) dst[n][k] = *(const LAS bf16x8*)(lds + PG8_SB(b, h) + boff + n * 2048 + k * 1024); } while (0)
; #define PG8_MMA(ai, bj, At, Bt) do { __builtin_amdgcn_s_setprio(1); _Pragma("unroll") for (int m = 0; m < 4; ++m) _Pragma("unroll") for (int n = 0; n < 2; ++n) _Pragma("unroll") for (int k = 0; k < 2; ++k) \
;         acc[ai][bj][m][n] = __builtin_amdgcn_mfma_f32_16x16x32_bf16(Bt[n][k], At[m][k], acc[ai][bj][m][n], 0, 0, 0); __builtin_amdgcn_s_setprio(0); } while (0)
; #define PG8_WAIT_V(n) asm volatile("s_waitcnt vmcnt(" #n ")" ::: "memory")
; #define PG8_WAIT_L(n) asm volatile("s_waitcnt lgkmcnt(" #n ")" ::: "memory")
; #define PG8_BAR __builtin_amdgcn_s_barrier()
; #define PG8_SCHED __builtin_amdgcn_sched_barrier(0)
; template <class Epi, bool ALIGN_EPI, bool SP2 = PG8_SP2_DEFAULT>
; __device__ __forceinline__ void gemm_phase(LAS unsigned char* lds, const Gemm g, const StaticOrder& S, const Epi& E) {
;     ...
;             PG8_WAIT_V(8); PG8_WAIT_L(0); PG8_BAR; PG8_MMA(1, 0, At, B0); PG8_MMA(1, 1, At, B1); PG8_BAR; PG8_SCHED;
;             PG8_LDB(B0, 1, 0); PG8_LDB(B1, 1, 1); PG8_SCHED; PG8_LDA(At, 1, 0); PG8_STAGE(PG8_SA(0, 1), a2 + hstepA, voffA);
;             PG8_WAIT_V(8); PG8_WAIT_L(0); PG8_BAR; PG8_MMA(0, 0, At, B0); PG8_MMA(0, 1, At, B1); PG8_BAR; PG8_SCHED;
	v_mfma_f32_16x16x32_bf16 v[60:63], v[144:147], v[184:187], v[60:63]
	v_mfma_f32_16x16x32_bf16 v[56:59], v[160:163], v[184:187], v[56:59]
	v_mfma_f32_16x16x32_bf16 v[44:47], v[144:147], v[192:195], v[44:47]
	v_mfma_f32_16x16x32_bf16 v[40:43], v[160:163], v[192:195], v[40:43]
	v_mfma_f32_16x16x32_bf16 v[28:31], v[144:147], v[200:203], v[28:31]
	v_mfma_f32_16x16x32_bf16 v[24:27], v[160:163], v[200:203], v[24:27]
	v_mfma_f32_16x16x32_bf16 v[12:15], v[144:147], v[208:211], v[12:15]
	v_mfma_f32_16x16x32_bf16 v[8:11], v[160:163], v[208:211], v[8:11]
	v_mfma_f32_16x16x32_bf16 v[60:63], v[156:159], v[188:191], v[60:63]
	v_mfma_f32_16x16x32_bf16 v[56:59], v[164:167], v[188:191], v[56:59]
	v_mfma_f32_16x16x32_bf16 v[44:47], v[156:159], v[196:199], v[44:47]
	v_mfma_f32_16x16x32_bf16 v[40:43], v[164:167], v[196:199], v[40:43]
	v_mfma_f32_16x16x32_bf16 v[28:31], v[156:159], v[204:207], v[28:31]
	v_mfma_f32_16x16x32_bf16 v[24:27], v[164:167], v[204:207], v[24:27]
	v_mfma_f32_16x16x32_bf16 v[12:15], v[156:159], v[212:215], v[12:15]
	v_mfma_f32_16x16x32_bf16 v[8:11], v[164:167], v[212:215], v[8:11]
	v_mfma_f32_16x16x32_bf16 v[52:55], v[168:171], v[184:187], v[52:55]
	v_mfma_f32_16x16x32_bf16 v[48:51], v[176:179], v[184:187], v[48:51]
	v_mfma_f32_16x16x32_bf16 v[36:39], v[168:171], v[192:195], v[36:39]
	v_mfma_f32_16x16x32_bf16 v[32:35], v[176:179], v[192:195], v[32:35]
	v_mfma_f32_16x16x32_bf16 v[20:23], v[168:171], v[200:203], v[20:23]
	v_mfma_f32_16x16x32_bf16 v[16:19], v[176:179], v[200:203], v[16:19]
	v_mfma_f32_16x16x32_bf16 v[4:7], v[168:171], v[208:211], v[4:7]
	v_mfma_f32_16x16x32_bf16 v[0:3], v[176:179], v[208:211], v[0:3]
	v_mfma_f32_16x16x32_bf16 v[52:55], v[172:175], v[188:191], v[52:55]
	v_mfma_f32_16x16x32_bf16 v[48:51], v[180:183], v[188:191], v[48:51]
	v_mfma_f32_16x16x32_bf16 v[36:39], v[172:175], v[196:199], v[36:39]
	v_mfma_f32_16x16x32_bf16 v[32:35], v[180:183], v[196:199], v[32:35]
	v_mfma_f32_16x16x32_bf16 v[20:23], v[172:175], v[204:207], v[20:23]
	v_mfma_f32_16x16x32_bf16 v[16:19], v[180:183], v[204:207], v[16:19]
	s_setprio 0
	v_mfma_f32_16x16x32_bf16 v[4:7], v[172:175], v[212:215], v[4:7]
	v_mfma_f32_16x16x32_bf16 v[0:3], v[180:183], v[212:215], v[0:3]
	s_barrier
	s_add_i32 s50, 0, 0x18000
	s_add_i32 s51, 0, 0x1c000
	v_add_u32_e32 v164, s50, v151
	v_add_u32_e32 v180, s51, v151
	ds_read_b128 v[144:147], v164
	ds_read_b128 v[156:159], v164 offset:1024
	ds_read_b128 v[160:163], v164 offset:2048
	ds_read_b128 v[164:167], v164 offset:3072
	ds_read_b128 v[168:171], v180
	ds_read_b128 v[172:175], v180 offset:1024
	ds_read_b128 v[176:179], v180 offset:2048
	ds_read_b128 v[180:183], v180 offset:3072
	s_add_u32 s20, s26, 0x2b0000
	s_addc_u32 s21, s27, 0
	s_mov_b32 m0, s34
	v_lshl_add_u64 v[222:223], s[20:21], 0, v[128:129]
	ds_read_b128 v[184:187], v155 offset:32768
	ds_read_b128 v[188:191], v155 offset:33792
	ds_read_b128 v[192:195], v155 offset:34816
	ds_read_b128 v[196:199], v155 offset:35840
	ds_read_b128 v[200:203], v155 offset:36864
	ds_read_b128 v[204:207], v155 offset:37888
	ds_read_b128 v[208:211], v155 offset:38912
	ds_read_b128 v[212:215], v155 offset:39936
	global_load_lds_dwordx4 v[222:223], off
	v_lshl_add_u64 v[222:223], s[20:21], 0, v[132:133]
	s_mov_b32 m0, s35
	s_nop 0
	global_load_lds_dwordx4 v[222:223], off
	s_waitcnt vmcnt(8)
	s_waitcnt lgkmcnt(0)
	s_setprio 1
	s_barrier
	v_mfma_f32_16x16x32_bf16 v[124:127], v[144:147], v[184:187], v[124:127]
	v_mfma_f32_16x16x32_bf16 v[120:123], v[160:163], v[184:187], v[120:123]
	v_mfma_f32_16x16x32_bf16 v[108:111], v[144:147], v[192:195], v[108:111]
	v_mfma_f32_16x16x32_bf16 v[104:107], v[160:163], v[192:195], v[104:107]
	v_mfma_f32_16x16x32_bf16 v[92:95], v[144:147], v[200:203], v[92:95]
	v_mfma_f32_16x16x32_bf16 v[88:91], v[160:163], v[200:203], v[88:91]
	v_mfma_f32_16x16x32_bf16 v[76:79], v[144:147], v[208:211], v[76:79]
	v_mfma_f32_16x16x32_bf16 v[72:75], v[160:163], v[208:211], v[72:75]
	v_mfma_f32_16x16x32_bf16 v[124:127], v[156:159], v[188:191], v[124:127]
	v_mfma_f32_16x16x32_bf16 v[120:123], v[164:167], v[188:191], v[120:123]
	v_mfma_f32_16x16x32_bf16 v[108:111], v[156:159], v[196:199], v[108:111]
	v_mfma_f32_16x16x32_bf16 v[104:107], v[164:167], v[196:199], v[104:107]
	v_mfma_f32_16x16x32_bf16 v[92:95], v[156:159], v[204:207], v[92:95]
	v_mfma_f32_16x16x32_bf16 v[88:91], v[164:167], v[204:207], v[88:91]
	v_mfma_f32_16x16x32_bf16 v[76:79], v[156:159], v[212:215], v[76:79]
	v_mfma_f32_16x16x32_bf16 v[72:75], v[164:167], v[212:215], v[72:75]
	v_mfma_f32_16x16x32_bf16 v[116:119], v[168:171], v[184:187], v[116:119]
	v_mfma_f32_16x16x32_bf16 v[112:115], v[176:179], v[184:187], v[112:115]
	v_mfma_f32_16x16x32_bf16 v[100:103], v[168:171], v[192:195], v[100:103]
	v_mfma_f32_16x16x32_bf16 v[96:99], v[176:179], v[192:195], v[96:99]
	v_mfma_f32_16x16x32_bf16 v[84:87], v[168:171], v[200:203], v[84:87]
	v_mfma_f32_16x16x32_bf16 v[80:83], v[176:179], v[200:203], v[80:83]
	v_mfma_f32_16x16x32_bf16 v[68:71], v[168:171], v[208:211], v[68:71]
	v_mfma_f32_16x16x32_bf16 v[64:67], v[176:179], v[208:211], v[64:67]
	v_mfma_f32_16x16x32_bf16 v[116:119], v[172:175], v[188:191], v[116:119]
	v_mfma_f32_16x16x32_bf16 v[112:115], v[180:183], v[188:191], v[112:115]
	v_mfma_f32_16x16x32_bf16 v[100:103], v[172:175], v[196:199], v[100:103]
	v_mfma_f32_16x16x32_bf16 v[96:99], v[180:183], v[196:199], v[96:99]
	v_mfma_f32_16x16x32_bf16 v[84:87], v[172:175], v[204:207], v[84:87]
	v_mfma_f32_16x16x32_bf16 v[80:83], v[180:183], v[204:207], v[80:83]
	s_setprio 0
	v_mfma_f32_16x16x32_bf16 v[68:71], v[172:175], v[212:215], v[68:71]
	v_mfma_f32_16x16x32_bf16 v[64:67], v[180:183], v[212:215], v[64:67]
	s_barrier
; #define PG8_STAGE(bufoff, gbase, voff) do { _Pragma("unroll") for (int _i = 0; _i < 2; ++_i) \
;         __builtin_amdgcn_global_load_lds((const unsigned*)((const char*)(gbase) + (voff)[_i]), (LAS unsigned*)(lds + (bufoff) + ldsw + _i * 8192), 16, 0, 0); } while (0)
; #define PG8_LDA(dst, b, h) do { _Pragma("unroll") for (int m = 0; m < 4; ++m) _Pragma("unroll") for (int k = 0; k < 2; ++k) dst[m][k] = *(const LAS bf16x8*)(lds + PG8_SA(b, h) + aoff + m * 2048 + k * 1024); } while (0)
; #define PG8_MMA(ai, bj, At, Bt) do { __builtin_amdgcn_s_setprio(1); _Pragma("unroll") for (int m = 0; m < 4; ++m) _Pragma("unroll") for (int n = 0; n < 2; ++n) _Pragma("unroll") for (int k = 0; k < 2; ++k) \
;         acc[ai][bj][m][n] = __builtin_amdgcn_mfma_f32_16x16x32_bf16(Bt[n][k], At[m][k], acc[ai][bj][m][n], 0, 0, 0); __builtin_amdgcn_s_setprio(0); } while (0)
; #define PG8_WAIT_V(n) asm volatile("s_waitcnt vmcnt(" #n ")" ::: "memory")
; #define PG8_WAIT_L(n) asm volatile("s_waitcnt lgkmcnt(" #n ")" ::: "memory")
; #define PG8_BAR __builtin_amdgcn_s_barrier()
; #define PG8_SCHED __builtin_amdgcn_sched_barrier(0)
; template <class Epi, bool ALIGN_EPI, bool SP2 = PG8_SP2_DEFAULT>
; __device__ __forceinline__ void gemm_phase(LAS unsigned char* lds, const Gemm g, const StaticOrder& S, const Epi& E) {
;     ...
;         for (int t = 0; t < nt; t += 2) {
;             const bool last = (t == nt - 2);
;     ...
;             PG8_LDA(At, 1, 1); PG8_STAGE(PG8_SB(1, 0), b3, voffB); PG8_STAGE(PG8_SB(1, 1), b3 + hstepB, voffB); PG8_STAGE(PG8_SA(1, 0), a3, voffA);
;             PG8_WAIT_V(8); PG8_WAIT_L(0); PG8_BAR; PG8_MMA(1, 0, At, B0); PG8_MMA(1, 1, At, B1); PG8_BAR; PG8_SCHED;
	s_add_i32 s20, s50, s28
	v_lshl_add_u64 v[148:149], v[148:149], 0, s[6:7]
	s_mov_b32 m0, s20
	ds_read_b128 v[184:187], v155 offset:49152
	ds_read_b128 v[188:191], v155 offset:50176
	ds_read_b128 v[192:195], v155 offset:51200
	ds_read_b128 v[196:199], v155 offset:52224
	ds_read_b128 v[200:203], v155 offset:53248
	ds_read_b128 v[204:207], v155 offset:54272
	ds_read_b128 v[208:211], v155 offset:55296
	ds_read_b128 v[212:215], v155 offset:56320
	global_load_lds_dwordx4 v[148:149], off
	s_add_i32 m0, s20, 0x2000
	s_add_u32 s20, s24, 0x2b0080
	v_lshl_add_u64 v[148:149], v[216:217], 0, s[6:7]
	s_addc_u32 s21, s25, 0
	s_add_i32 s24, s51, s28
	global_load_lds_dwordx4 v[148:149], off
	v_lshl_add_u64 v[148:149], s[20:21], 0, v[130:131]
	s_mov_b32 m0, s24
	s_nop 0
	global_load_lds_dwordx4 v[148:149], off
	v_lshl_add_u64 v[148:149], s[20:21], 0, v[134:135]
	s_add_i32 m0, s24, 0x2000
	s_nop 0
	global_load_lds_dwordx4 v[148:149], off
	v_lshl_add_u64 v[148:149], v[218:219], 0, s[6:7]
	s_mov_b32 m0, s37
	s_nop 0
	global_load_lds_dwordx4 v[148:149], off
	v_lshl_add_u64 v[148:149], v[220:221], 0, s[6:7]
	s_mov_b32 m0, s38
	s_nop 0
	global_load_lds_dwordx4 v[148:149], off
	s_waitcnt vmcnt(8)
	s_waitcnt lgkmcnt(0)
	s_setprio 1
	s_barrier
	v_mfma_f32_16x16x32_bf16 v[60:63], v[144:147], v[184:187], v[60:63]
	v_mfma_f32_16x16x32_bf16 v[56:59], v[160:163], v[184:187], v[56:59]
	v_mfma_f32_16x16x32_bf16 v[44:47], v[144:147], v[192:195], v[44:47]
	v_mfma_f32_16x16x32_bf16 v[40:43], v[160:163], v[192:195], v[40:43]
	v_mfma_f32_16x16x32_bf16 v[28:31], v[144:147], v[200:203], v[28:31]
	v_mfma_f32_16x16x32_bf16 v[24:27], v[160:163], v[200:203], v[24:27]
	v_mfma_f32_16x16x32_bf16 v[12:15], v[144:147], v[208:211], v[12:15]
	v_mfma_f32_16x16x32_bf16 v[8:11], v[160:163], v[208:211], v[8:11]
	v_mfma_f32_16x16x32_bf16 v[60:63], v[156:159], v[188:191], v[60:63]
	v_mfma_f32_16x16x32_bf16 v[56:59], v[164:167], v[188:191], v[56:59]
	v_mfma_f32_16x16x32_bf16 v[44:47], v[156:159], v[196:199], v[44:47]
	v_mfma_f32_16x16x32_bf16 v[40:43], v[164:167], v[196:199], v[40:43]
	v_mfma_f32_16x16x32_bf16 v[28:31], v[156:159], v[204:207], v[28:31]
	v_mfma_f32_16x16x32_bf16 v[24:27], v[164:167], v[204:207], v[24:27]
	v_mfma_f32_16x16x32_bf16 v[12:15], v[156:159], v[212:215], v[12:15]
	v_mfma_f32_16x16x32_bf16 v[8:11], v[164:167], v[212:215], v[8:11]
	v_mfma_f32_16x16x32_bf16 v[52:55], v[168:171], v[184:187], v[52:55]
	v_mfma_f32_16x16x32_bf16 v[48:51], v[176:179], v[184:187], v[48:51]
	v_mfma_f32_16x16x32_bf16 v[36:39], v[168:171], v[192:195], v[36:39]
	v_mfma_f32_16x16x32_bf16 v[32:35], v[176:179], v[192:195], v[32:35]
	v_mfma_f32_16x16x32_bf16 v[20:23], v[168:171], v[200:203], v[20:23]
	v_mfma_f32_16x16x32_bf16 v[16:19], v[176:179], v[200:203], v[16:19]
	v_mfma_f32_16x16x32_bf16 v[4:7], v[168:171], v[208:211], v[4:7]
	v_mfma_f32_16x16x32_bf16 v[0:3], v[176:179], v[208:211], v[0:3]
	v_mfma_f32_16x16x32_bf16 v[52:55], v[172:175], v[188:191], v[52:55]
	v_mfma_f32_16x16x32_bf16 v[48:51], v[180:183], v[188:191], v[48:51]
	v_mfma_f32_16x16x32_bf16 v[36:39], v[172:175], v[196:199], v[36:39]
	v_mfma_f32_16x16x32_bf16 v[32:35], v[180:183], v[196:199], v[32:35]
	v_mfma_f32_16x16x32_bf16 v[20:23], v[172:175], v[204:207], v[20:23]
	v_mfma_f32_16x16x32_bf16 v[16:19], v[180:183], v[204:207], v[16:19]
	s_setprio 0
	v_mfma_f32_16x16x32_bf16 v[4:7], v[172:175], v[212:215], v[4:7]
	v_mfma_f32_16x16x32_bf16 v[0:3], v[180:183], v[212:215], v[0:3]
	s_barrier
	s_add_i32 s49, s49, 2
	s_add_u32 s47, s47, 0x100
	s_addc_u32 s48, s48, 0
	s_cmpk_gt_u32 s49, 0xa9
	s_mov_b64 s[20:21], s[22:23]
	s_cbranch_scc0 .LBB0_804
	s_and_b64 vcc, exec, s[8:9]
	s_cbranch_vccz .LBB0_807
	s_barrier
